# prologue fence v1 plus nt (non-temporal) hint on the 64 in-projection epilogue stores (ACT / Z,Bg / Q,K,Vt are written once and read in a later phase)
# baseline (speedup 1.0000x reference)
;     __device__ __forceinline__ void operator()(const f32x4 (&acc)[2][2][4][2], const Unit& u, int wr, int wc, int fr, int fq) const {
;     ...
;             for (int m = 0; m < 4; ++m) {
;                 const int row = row0 + ai * HALF + m * 16;
;                 const float rs = rt.get(ai, m, fr), rsl = rs * -LOG2E_F, irs2 = __builtin_amdgcn_rcpf(rs * rs);
;                 float o[8];
; #pragma unroll
;                 for (int n = 0; n < 2; ++n) {
;                     const f32x4 a = acc[ai][0][m][n], b = acc[ai][1][m][n];
;                     const f32x4 t = a * rsl, ab = a * b;
;                     f32x4 e; e[0] = __builtin_amdgcn_exp2f(t[0]); e[1] = __builtin_amdgcn_exp2f(t[1]); e[2] = __builtin_amdgcn_exp2f(t[2]); e[3] = __builtin_amdgcn_exp2f(t[3]);
;                     const f32x4 d = e * irs2 + irs2;
;                     f32x4 r; r[0] = __builtin_amdgcn_rcpf(d[0]); r[1] = __builtin_amdgcn_rcpf(d[1]); r[2] = __builtin_amdgcn_rcpf(d[2]); r[3] = __builtin_amdgcn_rcpf(d[3]);
;                     const f32x4 q = ab * r;
;                     o[n * 4 + 0] = q[0]; o[n * 4 + 1] = q[1]; o[n * 4 + 2] = q[2]; o[n * 4 + 3] = q[3];
;                 }
;                 { const u32x4 pk_ = pack8(o); *(u32x4*)(O + (size_t)row * ldo + col0) = pk_;
.LBB0_115:
	v_lshl_add_u32 v146, v145, 2, s3
	ds_read2_b32 v[148:149], v146 offset1:16
	s_lshl_b32 s17, s60, 7
	s_or_b32 s17, s17, s55
	v_lshl_add_u32 v150, v147, 3, s17
	v_pk_mul_f32 v[124:125], v[128:129], v[124:125]
	s_waitcnt lgkmcnt(0)
	v_mul_f32_e32 v152, 0xbfb8aa3b, v148
	v_mul_f32_e32 v147, v148, v148
	v_pk_mul_f32 v[154:155], v[128:129], v[152:153] op_sel_hi:[1,0]
	v_pk_mul_f32 v[156:157], v[126:127], v[152:153] op_sel_hi:[1,0]
	v_rcp_f32_e32 v148, v147
	v_exp_f32_e32 v156, v156
	v_exp_f32_e32 v154, v154
	v_exp_f32_e32 v155, v155
	v_exp_f32_e32 v157, v157
	v_pk_mul_f32 v[122:123], v[126:127], v[122:123]
	v_pk_mul_f32 v[114:115], v[118:119], v[114:115]
	v_pk_fma_f32 v[126:127], v[148:149], v[154:155], v[148:149] op_sel_hi:[0,1,0]
	v_pk_fma_f32 v[128:129], v[148:149], v[156:157], v[148:149] op_sel_hi:[0,1,0]
	v_pk_mul_f32 v[154:155], v[120:121], v[152:153] op_sel_hi:[1,0]
	v_pk_mul_f32 v[152:153], v[118:119], v[152:153] op_sel_hi:[1,0]
	v_rcp_f32_e32 v128, v128
	v_rcp_f32_e32 v129, v129
	v_exp_f32_e32 v152, v152
	v_exp_f32_e32 v153, v153
	v_rcp_f32_e32 v126, v126
	v_rcp_f32_e32 v127, v127
	v_exp_f32_e32 v154, v154
	v_exp_f32_e32 v155, v155
	v_pk_mul_f32 v[122:123], v[122:123], v[128:129]
	v_pk_fma_f32 v[128:129], v[148:149], v[152:153], v[148:149] op_sel_hi:[0,1,0]
	v_pk_mul_f32 v[124:125], v[124:125], v[126:127]
	v_pk_fma_f32 v[126:127], v[148:149], v[154:155], v[148:149] op_sel_hi:[0,1,0]
	v_rcp_f32_e32 v128, v128
	v_rcp_f32_e32 v129, v129
	v_rcp_f32_e32 v126, v126
	v_rcp_f32_e32 v127, v127
	v_pk_mul_f32 v[116:117], v[120:121], v[116:117]
	v_pk_mul_f32 v[114:115], v[114:115], v[128:129]
	v_add_u32_e32 v145, s15, v145
	v_ashrrev_i32_e32 v151, 31, v150
	v_pk_mul_f32 v[116:117], v[116:117], v[126:127]
	v_cvt_pk_bf16_f32 v120, v114, v115
	v_mov_b64_e32 v[114:115], s[24:25]
	v_cvt_pk_bf16_f32 v118, v122, v123
	v_cvt_pk_bf16_f32 v121, v116, v117
	v_mad_i64_i32 v[122:123], s[44:45], v145, s29, v[114:115]
	v_lshlrev_b64 v[116:117], 1, v[150:151]
	v_cvt_pk_bf16_f32 v119, v124, v125
	v_lshl_add_u64 v[122:123], v[122:123], 0, v[116:117]
	global_store_dwordx4 v[122:123], v[118:121], off nt
	v_pk_mul_f32 v[108:109], v[112:113], v[108:109]
	v_pk_mul_f32 v[106:107], v[110:111], v[106:107]
	v_mul_f32_e32 v118, 0xbfb8aa3b, v149
	v_mul_f32_e32 v119, v149, v149
	v_pk_mul_f32 v[122:123], v[112:113], v[118:119] op_sel_hi:[1,0]
	v_pk_mul_f32 v[124:125], v[110:111], v[118:119] op_sel_hi:[1,0]
	v_rcp_f32_e32 v120, v119
	v_exp_f32_e32 v124, v124
	v_exp_f32_e32 v122, v122
	v_exp_f32_e32 v123, v123
	v_exp_f32_e32 v125, v125
	v_pk_mul_f32 v[100:101], v[104:105], v[100:101]
	v_pk_mul_f32 v[98:99], v[102:103], v[98:99]
	v_pk_fma_f32 v[110:111], v[120:121], v[122:123], v[120:121] op_sel_hi:[0,1,0]
	v_pk_fma_f32 v[112:113], v[120:121], v[124:125], v[120:121] op_sel_hi:[0,1,0]
	v_pk_mul_f32 v[122:123], v[104:105], v[118:119] op_sel_hi:[1,0]
	v_pk_mul_f32 v[118:119], v[102:103], v[118:119] op_sel_hi:[1,0]
	v_rcp_f32_e32 v112, v112
	v_rcp_f32_e32 v113, v113
	v_rcp_f32_e32 v110, v110
	v_rcp_f32_e32 v111, v111
	v_exp_f32_e32 v118, v118
	v_exp_f32_e32 v122, v122
	v_exp_f32_e32 v123, v123
	v_exp_f32_e32 v119, v119
	v_pk_mul_f32 v[108:109], v[108:109], v[110:111]
	v_pk_mul_f32 v[106:107], v[106:107], v[112:113]
	v_pk_fma_f32 v[110:111], v[120:121], v[122:123], v[120:121] op_sel_hi:[0,1,0]
	v_pk_fma_f32 v[112:113], v[120:121], v[118:119], v[120:121] op_sel_hi:[0,1,0]
	v_rcp_f32_e32 v112, v112
	v_rcp_f32_e32 v110, v110
	v_rcp_f32_e32 v111, v111
	v_rcp_f32_e32 v113, v113
	v_add_u32_e32 v104, 16, v145
	v_mad_i64_i32 v[104:105], s[44:45], v104, s29, v[114:115]
	v_pk_mul_f32 v[102:103], v[100:101], v[110:111]
	v_pk_mul_f32 v[100:101], v[98:99], v[112:113]
	v_cvt_pk_bf16_f32 v98, v106, v107
	v_cvt_pk_bf16_f32 v100, v100, v101
	v_cvt_pk_bf16_f32 v101, v102, v103
	ds_read2_b32 v[102:103], v146 offset0:32 offset1:48
	v_cvt_pk_bf16_f32 v99, v108, v109
	v_lshl_add_u64 v[104:105], v[104:105], 0, v[116:117]
	global_store_dwordx4 v[104:105], v[98:101], off nt
	v_pk_mul_f32 v[92:93], v[96:97], v[92:93]
	v_pk_mul_f32 v[90:91], v[94:95], v[90:91]
	s_waitcnt lgkmcnt(0)
	v_mul_f32_e32 v98, 0xbfb8aa3b, v102
	v_mul_f32_e32 v99, v102, v102
	v_pk_mul_f32 v[104:105], v[96:97], v[98:99] op_sel_hi:[1,0]
	v_pk_mul_f32 v[106:107], v[94:95], v[98:99] op_sel_hi:[1,0]
	v_rcp_f32_e32 v100, v99
	v_exp_f32_e32 v106, v106
	v_exp_f32_e32 v104, v104
	v_exp_f32_e32 v105, v105
	v_exp_f32_e32 v107, v107
	v_pk_mul_f32 v[84:85], v[88:89], v[84:85]
	v_pk_mul_f32 v[82:83], v[86:87], v[82:83]
	v_pk_fma_f32 v[94:95], v[100:101], v[104:105], v[100:101] op_sel_hi:[0,1,0]
	v_pk_fma_f32 v[96:97], v[100:101], v[106:107], v[100:101] op_sel_hi:[0,1,0]
	v_pk_mul_f32 v[104:105], v[88:89], v[98:99] op_sel_hi:[1,0]
	v_pk_mul_f32 v[98:99], v[86:87], v[98:99] op_sel_hi:[1,0]
	v_rcp_f32_e32 v96, v96
	v_rcp_f32_e32 v97, v97
	v_rcp_f32_e32 v94, v94
	v_rcp_f32_e32 v95, v95
	v_exp_f32_e32 v98, v98
	v_exp_f32_e32 v104, v104
	v_exp_f32_e32 v105, v105
	v_exp_f32_e32 v99, v99
	v_pk_mul_f32 v[92:93], v[92:93], v[94:95]
	v_pk_mul_f32 v[90:91], v[90:91], v[96:97]
	v_pk_fma_f32 v[94:95], v[100:101], v[104:105], v[100:101] op_sel_hi:[0,1,0]
	v_pk_fma_f32 v[96:97], v[100:101], v[98:99], v[100:101] op_sel_hi:[0,1,0]
	v_rcp_f32_e32 v96, v96
	v_rcp_f32_e32 v94, v94
	v_rcp_f32_e32 v95, v95
	v_rcp_f32_e32 v97, v97
	v_add_u32_e32 v88, 32, v145
	v_pk_mul_f32 v[74:75], v[78:79], v[74:75]
	v_pk_mul_f32 v[86:87], v[84:85], v[94:95]
	v_pk_mul_f32 v[84:85], v[82:83], v[96:97]
	v_cvt_pk_bf16_f32 v82, v90, v91
	v_cvt_pk_bf16_f32 v84, v84, v85
	v_cvt_pk_bf16_f32 v85, v86, v87
	v_mad_i64_i32 v[86:87], s[44:45], v88, s29, v[114:115]
	v_cvt_pk_bf16_f32 v83, v92, v93
;     __device__ __forceinline__ void operator()(const f32x4 (&acc)[2][2][4][2], const Unit& u, int wr, int wc, int fr, int fq) const {
;     ...
;             for (int m = 0; m < 4; ++m) {
;                 const int row = row0 + ai * HALF + m * 16;
;                 const float rs = rt.get(ai, m, fr), rsl = rs * -LOG2E_F, irs2 = __builtin_amdgcn_rcpf(rs * rs);
;                 float o[8];
; #pragma unroll
;                 for (int n = 0; n < 2; ++n) {
;                     const f32x4 a = acc[ai][0][m][n], b = acc[ai][1][m][n];
;                     const f32x4 t = a * rsl, ab = a * b;
;                     f32x4 e; e[0] = __builtin_amdgcn_exp2f(t[0]); e[1] = __builtin_amdgcn_exp2f(t[1]); e[2] = __builtin_amdgcn_exp2f(t[2]); e[3] = __builtin_amdgcn_exp2f(t[3]);
;                     const f32x4 d = e * irs2 + irs2;
;                     f32x4 r; r[0] = __builtin_amdgcn_rcpf(d[0]); r[1] = __builtin_amdgcn_rcpf(d[1]); r[2] = __builtin_amdgcn_rcpf(d[2]); r[3] = __builtin_amdgcn_rcpf(d[3]);
;                     const f32x4 q = ab * r;
;                     o[n * 4 + 0] = q[0]; o[n * 4 + 1] = q[1]; o[n * 4 + 2] = q[2]; o[n * 4 + 3] = q[3];
;                 }
;                 { const u32x4 pk_ = pack8(o); *(u32x4*)(O + (size_t)row * ldo + col0) = pk_;
	v_lshl_add_u64 v[86:87], v[86:87], 0, v[116:117]
	global_store_dwordx4 v[86:87], v[82:85], off nt
	v_pk_mul_f32 v[72:73], v[76:77], v[72:73]
	v_pk_mul_f32 v[66:67], v[70:71], v[66:67]
	v_mul_f32_e32 v82, 0xbfb8aa3b, v103
	v_mul_f32_e32 v83, v103, v103
	v_pk_mul_f32 v[86:87], v[78:79], v[82:83] op_sel_hi:[1,0]
	v_pk_mul_f32 v[88:89], v[76:77], v[82:83] op_sel_hi:[1,0]
	v_rcp_f32_e32 v84, v83
	v_exp_f32_e32 v88, v88
	v_exp_f32_e32 v86, v86
	v_exp_f32_e32 v87, v87
	v_exp_f32_e32 v89, v89
	v_pk_mul_f32 v[64:65], v[68:69], v[64:65]
	v_pk_mul_f32 v[58:59], v[62:63], v[58:59]
	v_pk_fma_f32 v[76:77], v[84:85], v[86:87], v[84:85] op_sel_hi:[0,1,0]
	v_pk_fma_f32 v[78:79], v[84:85], v[88:89], v[84:85] op_sel_hi:[0,1,0]
	v_pk_mul_f32 v[86:87], v[70:71], v[82:83] op_sel_hi:[1,0]
	v_pk_mul_f32 v[82:83], v[68:69], v[82:83] op_sel_hi:[1,0]
	v_rcp_f32_e32 v78, v78
	v_rcp_f32_e32 v79, v79
	v_rcp_f32_e32 v76, v76
	v_rcp_f32_e32 v77, v77
	v_exp_f32_e32 v82, v82
	v_exp_f32_e32 v86, v86
	v_exp_f32_e32 v87, v87
	v_exp_f32_e32 v83, v83
	v_pk_mul_f32 v[74:75], v[74:75], v[76:77]
	v_pk_mul_f32 v[72:73], v[72:73], v[78:79]
	v_pk_fma_f32 v[76:77], v[84:85], v[86:87], v[84:85] op_sel_hi:[0,1,0]
	v_pk_fma_f32 v[78:79], v[84:85], v[82:83], v[84:85] op_sel_hi:[0,1,0]
	v_rcp_f32_e32 v78, v78
	v_rcp_f32_e32 v76, v76
	v_rcp_f32_e32 v77, v77
	v_rcp_f32_e32 v79, v79
	v_add_u32_e32 v70, 48, v145
	v_mad_i64_i32 v[70:71], s[44:45], v70, s29, v[114:115]
	v_pk_mul_f32 v[68:69], v[66:67], v[76:77]
	v_pk_mul_f32 v[66:67], v[64:65], v[78:79]
	v_cvt_pk_bf16_f32 v64, v72, v73
	v_cvt_pk_bf16_f32 v66, v66, v67
	v_cvt_pk_bf16_f32 v67, v68, v69
	ds_read2_b32 v[68:69], v146 offset0:64 offset1:80
	v_cvt_pk_bf16_f32 v65, v74, v75
	v_lshl_add_u64 v[70:71], v[70:71], 0, v[116:117]
	global_store_dwordx4 v[70:71], v[64:67], off nt
	v_pk_mul_f32 v[56:57], v[60:61], v[56:57]
	v_pk_mul_f32 v[50:51], v[54:55], v[50:51]
	s_waitcnt lgkmcnt(0)
	v_mul_f32_e32 v64, 0xbfb8aa3b, v68
	v_mul_f32_e32 v65, v68, v68
	v_pk_mul_f32 v[70:71], v[62:63], v[64:65] op_sel_hi:[1,0]
	v_pk_mul_f32 v[72:73], v[60:61], v[64:65] op_sel_hi:[1,0]
	v_rcp_f32_e32 v66, v65
	v_exp_f32_e32 v72, v72
	v_exp_f32_e32 v70, v70
	v_exp_f32_e32 v71, v71
	v_exp_f32_e32 v73, v73
	v_add_u32_e32 v67, 0x80, v145
	v_pk_mul_f32 v[48:49], v[52:53], v[48:49]
	v_pk_fma_f32 v[60:61], v[66:67], v[70:71], v[66:67] op_sel_hi:[0,1,0]
	v_pk_fma_f32 v[62:63], v[66:67], v[72:73], v[66:67] op_sel_hi:[0,1,0]
	v_pk_mul_f32 v[70:71], v[54:55], v[64:65] op_sel_hi:[1,0]
	v_pk_mul_f32 v[64:65], v[52:53], v[64:65] op_sel_hi:[1,0]
	v_rcp_f32_e32 v62, v62
	v_rcp_f32_e32 v63, v63
	v_rcp_f32_e32 v60, v60
	v_rcp_f32_e32 v61, v61
	v_exp_f32_e32 v64, v64
	v_exp_f32_e32 v70, v70
	v_exp_f32_e32 v71, v71
	v_exp_f32_e32 v65, v65
	v_pk_mul_f32 v[58:59], v[58:59], v[60:61]
	v_pk_mul_f32 v[56:57], v[56:57], v[62:63]
	v_pk_fma_f32 v[60:61], v[66:67], v[70:71], v[66:67] op_sel_hi:[0,1,0]
	v_pk_fma_f32 v[62:63], v[66:67], v[64:65], v[66:67] op_sel_hi:[0,1,0]
	v_rcp_f32_e32 v62, v62
	v_rcp_f32_e32 v60, v60
	v_rcp_f32_e32 v61, v61
	v_rcp_f32_e32 v63, v63
	v_pk_mul_f32 v[42:43], v[46:47], v[42:43]
	v_pk_mul_f32 v[40:41], v[44:45], v[40:41]
	v_pk_mul_f32 v[52:53], v[50:51], v[60:61]
	v_pk_mul_f32 v[50:51], v[48:49], v[62:63]
	v_cvt_pk_bf16_f32 v48, v56, v57
	v_cvt_pk_bf16_f32 v50, v50, v51
	v_cvt_pk_bf16_f32 v51, v52, v53
	v_mad_i64_i32 v[52:53], s[44:45], v67, s29, v[114:115]
	v_cvt_pk_bf16_f32 v49, v58, v59
	v_lshl_add_u64 v[52:53], v[52:53], 0, v[116:117]
	global_store_dwordx4 v[52:53], v[48:51], off nt
	v_pk_mul_f32 v[34:35], v[38:39], v[34:35]
	v_pk_mul_f32 v[32:33], v[36:37], v[32:33]
	v_mul_f32_e32 v48, 0xbfb8aa3b, v69
	v_mul_f32_e32 v49, v69, v69
	v_pk_mul_f32 v[52:53], v[46:47], v[48:49] op_sel_hi:[1,0]
	v_pk_mul_f32 v[54:55], v[44:45], v[48:49] op_sel_hi:[1,0]
	v_rcp_f32_e32 v50, v49
	v_exp_f32_e32 v54, v54
	v_exp_f32_e32 v52, v52
	v_exp_f32_e32 v53, v53
	v_exp_f32_e32 v55, v55
	v_pk_mul_f32 v[26:27], v[30:31], v[26:27]
	v_pk_mul_f32 v[24:25], v[28:29], v[24:25]
	v_pk_fma_f32 v[44:45], v[50:51], v[52:53], v[50:51] op_sel_hi:[0,1,0]
	v_pk_fma_f32 v[46:47], v[50:51], v[54:55], v[50:51] op_sel_hi:[0,1,0]
	v_pk_mul_f32 v[52:53], v[38:39], v[48:49] op_sel_hi:[1,0]
	v_pk_mul_f32 v[48:49], v[36:37], v[48:49] op_sel_hi:[1,0]
	v_rcp_f32_e32 v46, v46
	v_rcp_f32_e32 v47, v47
	v_rcp_f32_e32 v44, v44
	v_rcp_f32_e32 v45, v45
	v_exp_f32_e32 v48, v48
	v_exp_f32_e32 v52, v52
	v_exp_f32_e32 v53, v53
	v_exp_f32_e32 v49, v49
	v_pk_mul_f32 v[42:43], v[42:43], v[44:45]
	v_pk_mul_f32 v[40:41], v[40:41], v[46:47]
	v_pk_fma_f32 v[44:45], v[50:51], v[52:53], v[50:51] op_sel_hi:[0,1,0]
	v_pk_fma_f32 v[46:47], v[50:51], v[48:49], v[50:51] op_sel_hi:[0,1,0]
	v_rcp_f32_e32 v46, v46
	v_rcp_f32_e32 v44, v44
	v_rcp_f32_e32 v45, v45
	v_rcp_f32_e32 v47, v47
	v_add_u32_e32 v38, 0x90, v145
	v_mad_i64_i32 v[38:39], s[44:45], v38, s29, v[114:115]
	v_pk_mul_f32 v[36:37], v[34:35], v[44:45]
	v_pk_mul_f32 v[34:35], v[32:33], v[46:47]
	v_cvt_pk_bf16_f32 v32, v40, v41
	v_cvt_pk_bf16_f32 v34, v34, v35
	v_cvt_pk_bf16_f32 v35, v36, v37
	ds_read2_b32 v[36:37], v146 offset0:96 offset1:112
	v_cvt_pk_bf16_f32 v33, v42, v43
	v_lshl_add_u64 v[38:39], v[38:39], 0, v[116:117]
	global_store_dwordx4 v[38:39], v[32:35], off nt
	v_pk_mul_f32 v[18:19], v[22:23], v[18:19]
	v_pk_mul_f32 v[16:17], v[20:21], v[16:17]
	s_waitcnt lgkmcnt(0)
;     __device__ __forceinline__ void operator()(const f32x4 (&acc)[2][2][4][2], const Unit& u, int wr, int wc, int fr, int fq) const {
;     ...
;             for (int m = 0; m < 4; ++m) {
;                 const int row = row0 + ai * HALF + m * 16;
;                 const float rs = rt.get(ai, m, fr), rsl = rs * -LOG2E_F, irs2 = __builtin_amdgcn_rcpf(rs * rs);
;                 float o[8];
; #pragma unroll
;                 for (int n = 0; n < 2; ++n) {
;                     const f32x4 a = acc[ai][0][m][n], b = acc[ai][1][m][n];
;                     const f32x4 t = a * rsl, ab = a * b;
;                     f32x4 e; e[0] = __builtin_amdgcn_exp2f(t[0]); e[1] = __builtin_amdgcn_exp2f(t[1]); e[2] = __builtin_amdgcn_exp2f(t[2]); e[3] = __builtin_amdgcn_exp2f(t[3]);
;                     const f32x4 d = e * irs2 + irs2;
;                     f32x4 r; r[0] = __builtin_amdgcn_rcpf(d[0]); r[1] = __builtin_amdgcn_rcpf(d[1]); r[2] = __builtin_amdgcn_rcpf(d[2]); r[3] = __builtin_amdgcn_rcpf(d[3]);
;                     const f32x4 q = ab * r;
;                     o[n * 4 + 0] = q[0]; o[n * 4 + 1] = q[1]; o[n * 4 + 2] = q[2]; o[n * 4 + 3] = q[3];
;                 }
;                 { const u32x4 pk_ = pack8(o); *(u32x4*)(O + (size_t)row * ldo + col0) = pk_;
	v_mul_f32_e32 v32, 0xbfb8aa3b, v36
	v_mul_f32_e32 v33, v36, v36
	v_pk_mul_f32 v[38:39], v[30:31], v[32:33] op_sel_hi:[1,0]
	v_pk_mul_f32 v[40:41], v[28:29], v[32:33] op_sel_hi:[1,0]
	v_rcp_f32_e32 v34, v33
	v_exp_f32_e32 v40, v40
	v_exp_f32_e32 v38, v38
	v_exp_f32_e32 v39, v39
	v_exp_f32_e32 v41, v41
	v_pk_mul_f32 v[10:11], v[14:15], v[10:11]
	v_pk_mul_f32 v[8:9], v[12:13], v[8:9]
	v_pk_fma_f32 v[28:29], v[34:35], v[38:39], v[34:35] op_sel_hi:[0,1,0]
	v_pk_fma_f32 v[30:31], v[34:35], v[40:41], v[34:35] op_sel_hi:[0,1,0]
	v_pk_mul_f32 v[38:39], v[22:23], v[32:33] op_sel_hi:[1,0]
	v_pk_mul_f32 v[32:33], v[20:21], v[32:33] op_sel_hi:[1,0]
	v_rcp_f32_e32 v30, v30
	v_rcp_f32_e32 v31, v31
	v_rcp_f32_e32 v28, v28
	v_rcp_f32_e32 v29, v29
	v_exp_f32_e32 v32, v32
	v_exp_f32_e32 v38, v38
	v_exp_f32_e32 v39, v39
	v_exp_f32_e32 v33, v33
	v_pk_mul_f32 v[26:27], v[26:27], v[28:29]
	v_pk_mul_f32 v[24:25], v[24:25], v[30:31]
	v_pk_fma_f32 v[28:29], v[34:35], v[38:39], v[34:35] op_sel_hi:[0,1,0]
	v_pk_fma_f32 v[30:31], v[34:35], v[32:33], v[34:35] op_sel_hi:[0,1,0]
	v_rcp_f32_e32 v30, v30
	v_rcp_f32_e32 v28, v28
	v_rcp_f32_e32 v29, v29
	v_rcp_f32_e32 v31, v31
	v_add_u32_e32 v22, 0xa0, v145
	v_pk_mul_f32 v[2:3], v[6:7], v[2:3]
	v_pk_mul_f32 v[20:21], v[18:19], v[28:29]
	v_pk_mul_f32 v[18:19], v[16:17], v[30:31]
	v_cvt_pk_bf16_f32 v16, v24, v25
	v_cvt_pk_bf16_f32 v18, v18, v19
	v_cvt_pk_bf16_f32 v19, v20, v21
	v_mad_i64_i32 v[20:21], s[44:45], v22, s29, v[114:115]
	v_cvt_pk_bf16_f32 v17, v26, v27
	v_lshl_add_u64 v[20:21], v[20:21], 0, v[116:117]
	global_store_dwordx4 v[20:21], v[16:19], off nt
	v_pk_mul_f32 v[0:1], v[4:5], v[0:1]
	s_andn2_b64 vcc, exec, s[4:5]
	v_mul_f32_e32 v16, 0xbfb8aa3b, v37
	v_mul_f32_e32 v17, v37, v37
	v_pk_mul_f32 v[20:21], v[14:15], v[16:17] op_sel_hi:[1,0]
	v_pk_mul_f32 v[22:23], v[12:13], v[16:17] op_sel_hi:[1,0]
	v_rcp_f32_e32 v18, v17
	v_exp_f32_e32 v22, v22
	v_exp_f32_e32 v20, v20
	v_exp_f32_e32 v21, v21
	v_exp_f32_e32 v23, v23
	s_mov_b64 s[4:5], -1
	v_pk_fma_f32 v[12:13], v[18:19], v[20:21], v[18:19] op_sel_hi:[0,1,0]
	v_pk_fma_f32 v[14:15], v[18:19], v[22:23], v[18:19] op_sel_hi:[0,1,0]
	v_pk_mul_f32 v[20:21], v[6:7], v[16:17] op_sel_hi:[1,0]
	v_pk_mul_f32 v[16:17], v[4:5], v[16:17] op_sel_hi:[1,0]
	v_rcp_f32_e32 v14, v14
	v_rcp_f32_e32 v15, v15
	v_rcp_f32_e32 v12, v12
	v_rcp_f32_e32 v13, v13
	v_exp_f32_e32 v16, v16
	v_exp_f32_e32 v20, v20
	v_exp_f32_e32 v21, v21
	v_exp_f32_e32 v17, v17
	v_pk_mul_f32 v[10:11], v[10:11], v[12:13]
	v_pk_mul_f32 v[8:9], v[8:9], v[14:15]
	v_pk_fma_f32 v[12:13], v[18:19], v[20:21], v[18:19] op_sel_hi:[0,1,0]
	v_pk_fma_f32 v[14:15], v[18:19], v[16:17], v[18:19] op_sel_hi:[0,1,0]
	v_rcp_f32_e32 v14, v14
	v_rcp_f32_e32 v12, v12
	v_rcp_f32_e32 v13, v13
	v_rcp_f32_e32 v15, v15
	v_add_u32_e32 v6, 0xb0, v145
	v_pk_mul_f32 v[4:5], v[2:3], v[12:13]
	v_pk_mul_f32 v[2:3], v[0:1], v[14:15]
	v_cvt_pk_bf16_f32 v0, v8, v9
	v_cvt_pk_bf16_f32 v2, v2, v3
	v_cvt_pk_bf16_f32 v3, v4, v5
	v_mad_i64_i32 v[4:5], s[44:45], v6, s29, v[114:115]
	v_cvt_pk_bf16_f32 v1, v10, v11
	v_lshl_add_u64 v[4:5], v[4:5], 0, v[116:117]
	global_store_dwordx4 v[4:5], v[0:3], off nt
	s_cbranch_vccnz .LBB0_106
	s_andn2_b64 vcc, exec, s[10:11]
	s_cbranch_vccnz .LBB0_105
	s_barrier
	s_branch .LBB0_105

;     __device__ __forceinline__ void operator()(const f32x4 (&acc)[2][2][4][2], const Unit& u, int wr, int wc, int fr, int fq) const {
;     ...
;             const int col0 = (u.pn - 8) * BM + wc * 32 + 8 * fq;
; #pragma unroll
;             for (int ai = 0; ai < 2; ++ai)
; #pragma unroll
;                 for (int m = 0; m < 4; ++m) {
;                     const int row = row0 + ai * HALF + m * 16;
;                     const float rs = rt.get(ai, m, fr);
; #pragma unroll
;                     for (int bj = 0; bj < 2; ++bj) {
;                         float o[8];
; #pragma unroll
;                         for (int n = 0; n < 2; ++n)
; #pragma unroll
;                             for (int j = 0; j < 4; ++j) o[n * 4 + j] = acc[ai][bj][m][n][j] * rs;
;                         *(u32x4*)(Bg + (size_t)row * 1024 + col0 + bj * HALF) = pack8(o);
;                     }
.LBB0_137:
	s_lshl_b32 s17, s63, 8
	v_lshlrev_b32_e32 v146, 3, v151
	s_waitcnt lgkmcnt(0)
	v_pk_mul_f32 v[152:153], v[126:127], v[144:145] op_sel_hi:[1,0]
	v_pk_mul_f32 v[154:155], v[128:129], v[144:145] op_sel_hi:[1,0]
	v_pk_mul_f32 v[160:161], v[124:125], v[144:145] op_sel_hi:[1,0]
	v_lshlrev_b64 v[156:157], 11, v[142:143]
	v_cvt_pk_bf16_f32 v152, v152, v153
	v_cvt_pk_bf16_f32 v153, v154, v155
	v_cvt_pk_bf16_f32 v155, v160, v161
	v_ashrrev_i32_e32 v147, 31, v146
	s_or_b32 s20, s58, s17
	ds_read2_b32 v[160:161], v150 offset0:16 offset1:32
	v_pk_mul_f32 v[158:159], v[122:123], v[144:145] op_sel_hi:[1,0]
	v_lshl_add_u64 v[156:157], s[0:1], 0, v[156:157]
	v_lshl_add_u64 v[146:147], s[20:21], 0, v[146:147]
	v_cvt_pk_bf16_f32 v154, v158, v159
	v_lshl_add_u64 v[146:147], v[146:147], 1, v[156:157]
	global_store_dwordx4 v[146:147], v[152:155], off offset:-4096 nt
	v_pk_mul_f32 v[156:157], v[110:111], v[144:145] op_sel_hi:[1,0]
	v_pk_mul_f32 v[158:159], v[112:113], v[144:145] op_sel_hi:[1,0]
	v_pk_mul_f32 v[152:153], v[118:119], v[144:145] op_sel_hi:[1,0]
	v_pk_mul_f32 v[154:155], v[120:121], v[144:145] op_sel_hi:[1,0]
	v_cvt_pk_bf16_f32 v152, v152, v153
	v_cvt_pk_bf16_f32 v153, v154, v155
	v_cvt_pk_bf16_f32 v154, v156, v157
	v_cvt_pk_bf16_f32 v155, v158, v159
	global_store_dwordx4 v[146:147], v[152:155], off offset:-3840 nt
	s_waitcnt lgkmcnt(0)
	v_pk_mul_f32 v[156:157], v[106:107], v[160:161] op_sel_hi:[1,0]
	v_pk_mul_f32 v[158:159], v[108:109], v[160:161] op_sel_hi:[1,0]
	v_pk_mul_f32 v[152:153], v[114:115], v[160:161] op_sel_hi:[1,0]
	v_pk_mul_f32 v[154:155], v[116:117], v[160:161] op_sel_hi:[1,0]
	s_mov_b64 s[46:47], 0x8000
	v_cvt_pk_bf16_f32 v152, v152, v153
	v_cvt_pk_bf16_f32 v153, v154, v155
	v_cvt_pk_bf16_f32 v154, v156, v157
	v_cvt_pk_bf16_f32 v155, v158, v159
	v_lshl_add_u64 v[156:157], v[146:147], 0, s[46:47]
	global_store_dwordx4 v[156:157], v[152:155], off offset:-4096 nt
	v_pk_mul_f32 v[158:159], v[94:95], v[160:161] op_sel_hi:[1,0]
	v_pk_mul_f32 v[176:177], v[96:97], v[160:161] op_sel_hi:[1,0]
	v_pk_mul_f32 v[152:153], v[102:103], v[160:161] op_sel_hi:[1,0]
	v_pk_mul_f32 v[154:155], v[104:105], v[160:161] op_sel_hi:[1,0]
	v_cvt_pk_bf16_f32 v152, v152, v153
	v_cvt_pk_bf16_f32 v153, v154, v155
	v_cvt_pk_bf16_f32 v154, v158, v159
	v_cvt_pk_bf16_f32 v155, v176, v177
	global_store_dwordx4 v[156:157], v[152:155], off offset:-3840 nt
	v_mov_b32_e32 v156, v161
	ds_read2_b32 v[176:177], v150 offset0:48 offset1:64
	v_pk_mul_f32 v[152:153], v[98:99], v[156:157] op_sel_hi:[1,0]
	v_pk_mul_f32 v[154:155], v[100:101], v[156:157] op_sel_hi:[1,0]
	v_pk_mul_f32 v[158:159], v[90:91], v[156:157] op_sel_hi:[1,0]
	v_pk_mul_f32 v[160:161], v[92:93], v[156:157] op_sel_hi:[1,0]
	s_mov_b64 s[46:47], 0x10000
	v_cvt_pk_bf16_f32 v152, v152, v153
	v_cvt_pk_bf16_f32 v153, v154, v155
	v_cvt_pk_bf16_f32 v154, v158, v159
	v_cvt_pk_bf16_f32 v155, v160, v161
	v_lshl_add_u64 v[158:159], v[146:147], 0, s[46:47]
	global_store_dwordx4 v[158:159], v[152:155], off offset:-4096 nt
	v_pk_mul_f32 v[160:161], v[76:77], v[156:157] op_sel_hi:[1,0]
	s_mov_b64 s[46:47], 0x18000
	v_pk_mul_f32 v[152:153], v[86:87], v[156:157] op_sel_hi:[1,0]
	v_pk_mul_f32 v[154:155], v[88:89], v[156:157] op_sel_hi:[1,0]
	v_pk_mul_f32 v[156:157], v[78:79], v[156:157] op_sel_hi:[1,0]
	v_cvt_pk_bf16_f32 v152, v152, v153
	v_cvt_pk_bf16_f32 v153, v154, v155
	v_cvt_pk_bf16_f32 v154, v160, v161
	v_cvt_pk_bf16_f32 v155, v156, v157
	global_store_dwordx4 v[158:159], v[152:155], off offset:-3840 nt
	s_waitcnt lgkmcnt(0)
	v_pk_mul_f32 v[156:157], v[72:73], v[176:177] op_sel_hi:[1,0]
	v_pk_mul_f32 v[158:159], v[74:75], v[176:177] op_sel_hi:[1,0]
	v_pk_mul_f32 v[152:153], v[82:83], v[176:177] op_sel_hi:[1,0]
	v_pk_mul_f32 v[154:155], v[84:85], v[176:177] op_sel_hi:[1,0]
	v_cvt_pk_bf16_f32 v152, v152, v153
	v_cvt_pk_bf16_f32 v153, v154, v155
	v_cvt_pk_bf16_f32 v154, v156, v157
	v_cvt_pk_bf16_f32 v155, v158, v159
	v_lshl_add_u64 v[156:157], v[146:147], 0, s[46:47]
	global_store_dwordx4 v[156:157], v[152:155], off offset:-4096 nt
	v_pk_mul_f32 v[158:159], v[64:65], v[176:177] op_sel_hi:[1,0]
	v_pk_mul_f32 v[160:161], v[66:67], v[176:177] op_sel_hi:[1,0]
	v_pk_mul_f32 v[152:153], v[68:69], v[176:177] op_sel_hi:[1,0]
	v_pk_mul_f32 v[154:155], v[70:71], v[176:177] op_sel_hi:[1,0]
	v_cvt_pk_bf16_f32 v152, v152, v153
	v_cvt_pk_bf16_f32 v153, v154, v155
	v_cvt_pk_bf16_f32 v154, v158, v159
	v_cvt_pk_bf16_f32 v155, v160, v161
	global_store_dwordx4 v[156:157], v[152:155], off offset:-3840 nt
	v_mov_b32_e32 v156, v177
	ds_read2_b32 v[176:177], v150 offset0:80 offset1:96
	v_pk_mul_f32 v[152:153], v[60:61], v[156:157] op_sel_hi:[1,0]
	v_pk_mul_f32 v[154:155], v[62:63], v[156:157] op_sel_hi:[1,0]
	v_pk_mul_f32 v[158:159], v[56:57], v[156:157] op_sel_hi:[1,0]
	v_pk_mul_f32 v[160:161], v[58:59], v[156:157] op_sel_hi:[1,0]
	s_mov_b64 s[46:47], 0x40000
	v_cvt_pk_bf16_f32 v152, v152, v153
	v_cvt_pk_bf16_f32 v153, v154, v155
	v_cvt_pk_bf16_f32 v154, v158, v159
	v_cvt_pk_bf16_f32 v155, v160, v161
	v_lshl_add_u64 v[158:159], v[146:147], 0, s[46:47]
	global_store_dwordx4 v[158:159], v[152:155], off offset:-4096 nt
	v_pk_mul_f32 v[160:161], v[44:45], v[156:157] op_sel_hi:[1,0]
	s_mov_b64 s[46:47], 0x48000
	v_pk_mul_f32 v[152:153], v[52:53], v[156:157] op_sel_hi:[1,0]
	v_pk_mul_f32 v[154:155], v[54:55], v[156:157] op_sel_hi:[1,0]
	v_pk_mul_f32 v[156:157], v[46:47], v[156:157] op_sel_hi:[1,0]
	v_cvt_pk_bf16_f32 v152, v152, v153
	v_cvt_pk_bf16_f32 v153, v154, v155
	v_cvt_pk_bf16_f32 v154, v160, v161
	v_cvt_pk_bf16_f32 v155, v156, v157
	global_store_dwordx4 v[158:159], v[152:155], off offset:-3840 nt
	s_waitcnt lgkmcnt(0)
;     __device__ __forceinline__ void operator()(const f32x4 (&acc)[2][2][4][2], const Unit& u, int wr, int wc, int fr, int fq) const {
;     ...
;             const int col0 = (u.pn - 8) * BM + wc * 32 + 8 * fq;
; #pragma unroll
;             for (int ai = 0; ai < 2; ++ai)
; #pragma unroll
;                 for (int m = 0; m < 4; ++m) {
;                     const int row = row0 + ai * HALF + m * 16;
;                     const float rs = rt.get(ai, m, fr);
; #pragma unroll
;                     for (int bj = 0; bj < 2; ++bj) {
;                         float o[8];
; #pragma unroll
;                         for (int n = 0; n < 2; ++n)
; #pragma unroll
;                             for (int j = 0; j < 4; ++j) o[n * 4 + j] = acc[ai][bj][m][n][j] * rs;
;                         *(u32x4*)(Bg + (size_t)row * 1024 + col0 + bj * HALF) = pack8(o);
;                     }
	v_pk_mul_f32 v[156:157], v[40:41], v[176:177] op_sel_hi:[1,0]
	v_pk_mul_f32 v[158:159], v[42:43], v[176:177] op_sel_hi:[1,0]
	v_pk_mul_f32 v[152:153], v[48:49], v[176:177] op_sel_hi:[1,0]
	v_pk_mul_f32 v[154:155], v[50:51], v[176:177] op_sel_hi:[1,0]
	v_cvt_pk_bf16_f32 v152, v152, v153
	v_cvt_pk_bf16_f32 v153, v154, v155
	v_cvt_pk_bf16_f32 v154, v156, v157
	v_cvt_pk_bf16_f32 v155, v158, v159
	v_lshl_add_u64 v[156:157], v[146:147], 0, s[46:47]
	global_store_dwordx4 v[156:157], v[152:155], off offset:-4096 nt
	v_pk_mul_f32 v[158:159], v[28:29], v[176:177] op_sel_hi:[1,0]
	v_pk_mul_f32 v[160:161], v[30:31], v[176:177] op_sel_hi:[1,0]
	v_pk_mul_f32 v[152:153], v[36:37], v[176:177] op_sel_hi:[1,0]
	v_pk_mul_f32 v[154:155], v[38:39], v[176:177] op_sel_hi:[1,0]
	v_cvt_pk_bf16_f32 v152, v152, v153
	v_cvt_pk_bf16_f32 v153, v154, v155
	v_cvt_pk_bf16_f32 v154, v158, v159
	v_cvt_pk_bf16_f32 v155, v160, v161
	global_store_dwordx4 v[156:157], v[152:155], off offset:-3840 nt
	v_mov_b32_e32 v156, v177
	ds_read_b32 v176, v150 offset:448
	v_pk_mul_f32 v[152:153], v[32:33], v[156:157] op_sel_hi:[1,0]
	v_pk_mul_f32 v[154:155], v[34:35], v[156:157] op_sel_hi:[1,0]
	v_pk_mul_f32 v[158:159], v[24:25], v[156:157] op_sel_hi:[1,0]
	v_pk_mul_f32 v[160:161], v[26:27], v[156:157] op_sel_hi:[1,0]
	s_mov_b64 s[46:47], 0x50000
	v_cvt_pk_bf16_f32 v152, v152, v153
	v_cvt_pk_bf16_f32 v153, v154, v155
	v_cvt_pk_bf16_f32 v154, v158, v159
	v_cvt_pk_bf16_f32 v155, v160, v161
	v_lshl_add_u64 v[158:159], v[146:147], 0, s[46:47]
	global_store_dwordx4 v[158:159], v[152:155], off offset:-4096 nt
	v_pk_mul_f32 v[160:161], v[12:13], v[156:157] op_sel_hi:[1,0]
	s_mov_b64 s[46:47], 0x58000
	v_pk_mul_f32 v[152:153], v[20:21], v[156:157] op_sel_hi:[1,0]
	v_pk_mul_f32 v[154:155], v[22:23], v[156:157] op_sel_hi:[1,0]
	v_pk_mul_f32 v[156:157], v[14:15], v[156:157] op_sel_hi:[1,0]
	v_cvt_pk_bf16_f32 v152, v152, v153
	v_cvt_pk_bf16_f32 v153, v154, v155
	v_cvt_pk_bf16_f32 v154, v160, v161
	v_cvt_pk_bf16_f32 v155, v156, v157
	global_store_dwordx4 v[158:159], v[152:155], off offset:-3840 nt
	s_waitcnt lgkmcnt(0)
	v_pk_mul_f32 v[156:157], v[8:9], v[176:177] op_sel_hi:[1,0]
	v_pk_mul_f32 v[158:159], v[10:11], v[176:177] op_sel_hi:[1,0]
	v_pk_mul_f32 v[152:153], v[16:17], v[176:177] op_sel_hi:[1,0]
	v_pk_mul_f32 v[154:155], v[18:19], v[176:177] op_sel_hi:[1,0]
	v_cvt_pk_bf16_f32 v152, v152, v153
	v_cvt_pk_bf16_f32 v153, v154, v155
	v_cvt_pk_bf16_f32 v154, v156, v157
	v_cvt_pk_bf16_f32 v155, v158, v159
	v_lshl_add_u64 v[146:147], v[146:147], 0, s[46:47]
	global_store_dwordx4 v[146:147], v[152:155], off offset:-4096 nt
	v_pk_mul_f32 v[156:157], v[0:1], v[176:177] op_sel_hi:[1,0]
	v_pk_mul_f32 v[158:159], v[2:3], v[176:177] op_sel_hi:[1,0]
	v_pk_mul_f32 v[152:153], v[4:5], v[176:177] op_sel_hi:[1,0]
	v_pk_mul_f32 v[154:155], v[6:7], v[176:177] op_sel_hi:[1,0]
	v_cvt_pk_bf16_f32 v152, v152, v153
	v_cvt_pk_bf16_f32 v153, v154, v155
	v_cvt_pk_bf16_f32 v154, v156, v157
	v_cvt_pk_bf16_f32 v155, v158, v159
	global_store_dwordx4 v[146:147], v[152:155], off offset:-3840 nt
	s_cbranch_execnz .LBB0_136
;     __device__ __forceinline__ void operator()(const f32x4 (&acc)[2][2][4][2], const Unit& u, int wr, int wc, int fr, int fq) const {
;     ...
;             const int col0 = u.pn * 128 + wc * 32 + 8 * fq;
; #pragma unroll
;             for (int ai = 0; ai < 2; ++ai)
; #pragma unroll
;                 for (int m = 0; m < 4; ++m) {
;                     const int row = row0 + ai * HALF + m * 16;
;                     const float rs = rt.get(ai, m, fr), rs2 = rs * rs;
;                     float o[8];
; #pragma unroll
;                     for (int n = 0; n < 2; ++n)
; #pragma unroll
;                         for (int j = 0; j < 4; ++j) o[n * 4 + j] = acc[ai][0][m][n][j] * acc[ai][1][m][n][j] * rs2;
;                     *(u32x4*)(Z + (size_t)row * 1024 + col0) = pack8(o);
;                 }
.LBB0_138:
	s_waitcnt lgkmcnt(0)
	v_mul_f32_e32 v144, v144, v144
	v_pk_mul_f32 v[118:119], v[126:127], v[118:119]
	v_pk_mul_f32 v[110:111], v[122:123], v[110:111]
	v_pk_mul_f32 v[118:119], v[118:119], v[144:145] op_sel_hi:[1,0]
	s_lshl_b32 s17, s63, 7
	v_pk_mul_f32 v[120:121], v[128:129], v[120:121]
	v_pk_mul_f32 v[122:123], v[110:111], v[144:145] op_sel_hi:[1,0]
	v_cvt_pk_bf16_f32 v110, v118, v119
	ds_read2_b32 v[118:119], v150 offset0:16 offset1:32
	s_or_b32 s17, s17, s58
	v_pk_mul_f32 v[120:121], v[120:121], v[144:145] op_sel_hi:[1,0]
	v_lshl_add_u32 v146, v151, 3, s17
	v_pk_mul_f32 v[112:113], v[124:125], v[112:113]
	v_cvt_pk_bf16_f32 v111, v120, v121
	v_lshlrev_b64 v[120:121], 11, v[142:143]
	v_ashrrev_i32_e32 v147, 31, v146
	v_pk_mul_f32 v[124:125], v[112:113], v[144:145] op_sel_hi:[1,0]
	v_lshl_add_u64 v[120:121], s[24:25], 0, v[120:121]
	v_cvt_pk_bf16_f32 v112, v122, v123
	v_cvt_pk_bf16_f32 v113, v124, v125
	v_lshl_add_u64 v[120:121], v[146:147], 1, v[120:121]
	global_store_dwordx4 v[120:121], v[110:113], off nt
	v_pk_mul_f32 v[102:103], v[114:115], v[102:103]
	v_pk_mul_f32 v[104:105], v[116:117], v[104:105]
	s_waitcnt lgkmcnt(0)
	v_mul_f32_e32 v110, v118, v118
	v_pk_mul_f32 v[102:103], v[102:103], v[110:111] op_sel_hi:[1,0]
	v_pk_mul_f32 v[96:97], v[108:109], v[96:97]
	v_pk_mul_f32 v[94:95], v[106:107], v[94:95]
	s_mov_b32 s17, 0x8000
	v_pk_mul_f32 v[104:105], v[104:105], v[110:111] op_sel_hi:[1,0]
	v_pk_mul_f32 v[106:107], v[94:95], v[110:111] op_sel_hi:[1,0]
	v_pk_mul_f32 v[108:109], v[96:97], v[110:111] op_sel_hi:[1,0]
	v_cvt_pk_bf16_f32 v94, v102, v103
	v_add_co_u32_e32 v102, vcc, s17, v120
	v_cvt_pk_bf16_f32 v95, v104, v105
	v_cvt_pk_bf16_f32 v96, v106, v107
	v_cvt_pk_bf16_f32 v97, v108, v109
	v_addc_co_u32_e32 v103, vcc, 0, v121, vcc
	global_store_dwordx4 v[102:103], v[94:97], off nt
	v_pk_mul_f32 v[86:87], v[98:99], v[86:87]
	v_pk_mul_f32 v[76:77], v[90:91], v[76:77]
	v_mul_f32_e32 v94, v119, v119
	v_pk_mul_f32 v[86:87], v[86:87], v[94:95] op_sel_hi:[1,0]
	v_pk_mul_f32 v[90:91], v[76:77], v[94:95] op_sel_hi:[1,0]
	v_cvt_pk_bf16_f32 v76, v86, v87
	ds_read2_b32 v[86:87], v150 offset0:48 offset1:64
	v_pk_mul_f32 v[88:89], v[100:101], v[88:89]
	v_pk_mul_f32 v[78:79], v[92:93], v[78:79]
	v_pk_mul_f32 v[88:89], v[88:89], v[94:95] op_sel_hi:[1,0]
	s_mov_b32 s17, 0x10000
	v_pk_mul_f32 v[92:93], v[78:79], v[94:95] op_sel_hi:[1,0]
	v_cvt_pk_bf16_f32 v77, v88, v89
	v_add_co_u32_e32 v88, vcc, s17, v120
	v_cvt_pk_bf16_f32 v78, v90, v91
	v_cvt_pk_bf16_f32 v79, v92, v93
	v_addc_co_u32_e32 v89, vcc, 0, v121, vcc
	global_store_dwordx4 v[88:89], v[76:79], off nt
	v_pk_mul_f32 v[68:69], v[82:83], v[68:69]
	v_pk_mul_f32 v[70:71], v[84:85], v[70:71]
	s_waitcnt lgkmcnt(0)
	v_mul_f32_e32 v76, v86, v86
	v_pk_mul_f32 v[68:69], v[68:69], v[76:77] op_sel_hi:[1,0]
	v_pk_mul_f32 v[66:67], v[74:75], v[66:67]
	v_pk_mul_f32 v[64:65], v[72:73], v[64:65]
	s_mov_b32 s17, 0x18000
	v_pk_mul_f32 v[70:71], v[70:71], v[76:77] op_sel_hi:[1,0]
	v_pk_mul_f32 v[72:73], v[64:65], v[76:77] op_sel_hi:[1,0]
	v_pk_mul_f32 v[74:75], v[66:67], v[76:77] op_sel_hi:[1,0]
	v_cvt_pk_bf16_f32 v64, v68, v69
	v_add_co_u32_e32 v68, vcc, s17, v120
	v_cvt_pk_bf16_f32 v65, v70, v71
	v_cvt_pk_bf16_f32 v66, v72, v73
	v_cvt_pk_bf16_f32 v67, v74, v75
	v_addc_co_u32_e32 v69, vcc, 0, v121, vcc
	global_store_dwordx4 v[68:69], v[64:67], off nt
	v_pk_mul_f32 v[52:53], v[60:61], v[52:53]
	v_pk_mul_f32 v[44:45], v[56:57], v[44:45]
	v_mul_f32_e32 v64, v87, v87
	v_pk_mul_f32 v[52:53], v[52:53], v[64:65] op_sel_hi:[1,0]
	v_pk_mul_f32 v[56:57], v[44:45], v[64:65] op_sel_hi:[1,0]
	v_cvt_pk_bf16_f32 v44, v52, v53
	ds_read2_b32 v[52:53], v150 offset0:80 offset1:96
	v_pk_mul_f32 v[54:55], v[62:63], v[54:55]
	v_pk_mul_f32 v[46:47], v[58:59], v[46:47]
	v_pk_mul_f32 v[54:55], v[54:55], v[64:65] op_sel_hi:[1,0]
	s_mov_b32 s17, 0x40000
	v_pk_mul_f32 v[58:59], v[46:47], v[64:65] op_sel_hi:[1,0]
	v_cvt_pk_bf16_f32 v45, v54, v55
	v_add_co_u32_e32 v54, vcc, s17, v120
	v_cvt_pk_bf16_f32 v46, v56, v57
	v_cvt_pk_bf16_f32 v47, v58, v59
	v_addc_co_u32_e32 v55, vcc, 0, v121, vcc
	global_store_dwordx4 v[54:55], v[44:47], off nt
	v_pk_mul_f32 v[36:37], v[48:49], v[36:37]
	v_pk_mul_f32 v[38:39], v[50:51], v[38:39]
	s_waitcnt lgkmcnt(0)
	v_mul_f32_e32 v44, v52, v52
	v_pk_mul_f32 v[36:37], v[36:37], v[44:45] op_sel_hi:[1,0]
	v_pk_mul_f32 v[30:31], v[42:43], v[30:31]
	v_pk_mul_f32 v[28:29], v[40:41], v[28:29]
	s_mov_b32 s17, 0x48000
	v_pk_mul_f32 v[38:39], v[38:39], v[44:45] op_sel_hi:[1,0]
	v_pk_mul_f32 v[40:41], v[28:29], v[44:45] op_sel_hi:[1,0]
	v_pk_mul_f32 v[42:43], v[30:31], v[44:45] op_sel_hi:[1,0]
	v_cvt_pk_bf16_f32 v28, v36, v37
	v_add_co_u32_e32 v36, vcc, s17, v120
	v_cvt_pk_bf16_f32 v29, v38, v39
	v_cvt_pk_bf16_f32 v30, v40, v41
	v_cvt_pk_bf16_f32 v31, v42, v43
	v_addc_co_u32_e32 v37, vcc, 0, v121, vcc
	global_store_dwordx4 v[36:37], v[28:31], off nt
	v_pk_mul_f32 v[22:23], v[34:35], v[22:23]
	v_pk_mul_f32 v[12:13], v[24:25], v[12:13]
	v_mul_f32_e32 v28, v53, v53
	v_pk_mul_f32 v[22:23], v[22:23], v[28:29] op_sel_hi:[1,0]
	v_pk_mul_f32 v[24:25], v[12:13], v[28:29] op_sel_hi:[1,0]
	v_cvt_pk_bf16_f32 v13, v22, v23
	ds_read_b32 v22, v150 offset:448
	v_pk_mul_f32 v[20:21], v[32:33], v[20:21]
	v_pk_mul_f32 v[14:15], v[26:27], v[14:15]
	v_pk_mul_f32 v[20:21], v[20:21], v[28:29] op_sel_hi:[1,0]
	s_mov_b32 s17, 0x50000
	v_pk_mul_f32 v[26:27], v[14:15], v[28:29] op_sel_hi:[1,0]
	v_cvt_pk_bf16_f32 v12, v20, v21
	v_add_co_u32_e32 v20, vcc, s17, v120
	v_cvt_pk_bf16_f32 v14, v24, v25
	v_cvt_pk_bf16_f32 v15, v26, v27
	v_addc_co_u32_e32 v21, vcc, 0, v121, vcc
	global_store_dwordx4 v[20:21], v[12:15], off nt
	v_pk_mul_f32 v[4:5], v[16:17], v[4:5]
	v_pk_mul_f32 v[6:7], v[18:19], v[6:7]
	s_waitcnt lgkmcnt(0)
	v_mul_f32_e32 v12, v22, v22
	v_pk_mul_f32 v[4:5], v[4:5], v[12:13] op_sel_hi:[1,0]
	v_pk_mul_f32 v[2:3], v[10:11], v[2:3]
	v_pk_mul_f32 v[0:1], v[8:9], v[0:1]
	v_pk_mul_f32 v[6:7], v[6:7], v[12:13] op_sel_hi:[1,0]
	v_pk_mul_f32 v[8:9], v[0:1], v[12:13] op_sel_hi:[1,0]
	v_pk_mul_f32 v[10:11], v[2:3], v[12:13] op_sel_hi:[1,0]
	v_cvt_pk_bf16_f32 v0, v4, v5
	v_add_co_u32_e32 v4, vcc, 0x58000, v120
	v_cvt_pk_bf16_f32 v1, v6, v7
	v_cvt_pk_bf16_f32 v2, v8, v9
	v_cvt_pk_bf16_f32 v3, v10, v11
	v_addc_co_u32_e32 v5, vcc, 0, v121, vcc
	global_store_dwordx4 v[4:5], v[0:3], off nt
	s_andn2_b64 vcc, exec, s[4:5]
	s_mov_b64 s[4:5], -1
	s_cbranch_vccnz .LBB0_125

;     __device__ __forceinline__ void operator()(const f32x4 (&acc)[2][2][4][2], const Unit& u, int wr, int wc, int fr, int fq) const {
;     ...
;             { const int tl = fr + 16 * fq; rt.tab[tl] = rstd_row(ssp, u.pn * BM + (tl >> 5) * HALF + wc * 32 + (tl & 31)); rt.cpm = -1; }
; #pragma unroll
;             for (int bj = 0; bj < 2; ++bj) {
;                 const int tok0 = u.pn * BM + bj * HALF + wc * 32 + 8 * fq, b = tok0 / seq, t = tok0 - b * seq;
;                 float rs[8];
; #pragma unroll
;                 for (int k = 0; k < 8; ++k) rs[k] = rt.tab[bj * 32 + 8 * fq + k];
; #pragma unroll
;                 for (int ai = 0; ai < 2; ++ai)
; #pragma unroll
;                     for (int m = 0; m < 4; ++m) {
;                         const int vc = ai * HALF + wr * 64 + m * 16 + fr;
;                         float o[8];
; #pragma unroll
;                         for (int n = 0; n < 2; ++n)
; #pragma unroll
;                             for (int j = 0; j < 4; ++j) o[n * 4 + j] = acc[ai][bj][m][n][j] * rs[n * 4 + j];
;                         *(u32x4*)(Vt + ((size_t)(b * 256 + vc)) * seq + t) = pack8(o);
;                     }
.LBB0_162:
	v_mov_b32_e32 v191, v81
	v_mov_b32_e32 v190, v198
	s_cmp_lg_u32 s20, 0
	s_cbranch_scc0 .LBB0_165
	v_lshl_add_u32 v130, v190, 4, v191
	v_lshlrev_b32_e32 v146, 2, v130
	s_lshl_b32 s5, s10, 8
	v_and_b32_e32 v131, 0xffffff80, v146
	v_add_u32_e32 v131, s5, v131
	v_and_b32_e32 v130, 31, v130
	v_or3_b32 v130, v131, v130, s60
	v_ashrrev_i32_e32 v131, 31, v130
	v_lshlrev_b64 v[130:131], 6, v[130:131]
	v_lshl_add_u64 v[142:143], s[26:27], 0, v[130:131]
	global_load_dwordx4 v[130:133], v[142:143], off offset:32
	global_load_dwordx4 v[134:137], v[142:143], off offset:48
	global_load_dwordx4 v[138:141], v[142:143], off
	s_nop 0
	global_load_dwordx4 v[142:145], v[142:143], off offset:16
	s_or_b32 s5, s5, s60
	s_waitcnt vmcnt(0)
	v_pk_add_f32 v[132:133], v[132:133], v[136:137]
	v_pk_add_f32 v[130:131], v[130:131], v[134:135]
	v_pk_add_f32 v[140:141], v[140:141], v[144:145]
	v_pk_add_f32 v[138:139], v[138:139], v[142:143]
	v_pk_add_f32 v[132:133], v[140:141], v[132:133]
	v_pk_add_f32 v[130:131], v[138:139], v[130:131]
	v_lshl_add_u32 v145, v190, 3, s5
	v_pk_mov_b32 v[134:135], v[130:131], v[132:133] op_sel:[1,0]
	v_mov_b32_e32 v131, v133
	v_pk_add_f32 v[130:131], v[134:135], v[130:131]
	v_add_u32_e32 v144, s59, v191
	v_add_f32_e32 v130, v130, v131
	v_fmamk_f32 v130, v130, 0x3a800000, v205
	v_rsq_f32_e32 v130, v130
	v_add_u32_e32 v131, s3, v146
	v_lshl_add_u32 v146, v190, 5, s3
	ds_write_b32 v131, v130
	v_ashrrev_i32_e32 v130, 31, v145
	v_lshrrev_b32_e32 v130, 18, v130
	v_add_u32_e32 v130, v145, v130
	v_ashrrev_i32_e32 v131, 14, v130
	v_and_b32_e32 v130, 0xffffc000, v130
	v_sub_u32_e32 v140, v145, v130
	v_lshl_add_u32 v138, v131, 8, v144
	ds_read_b128 v[134:137], v146
	ds_read_b128 v[130:133], v146 offset:16
	v_ashrrev_i32_e32 v139, 31, v138
	v_ashrrev_i32_e32 v141, 31, v140
	v_lshlrev_b64 v[140:141], 1, v[140:141]
	s_waitcnt lgkmcnt(1)
	v_pk_mul_f32 v[142:143], v[126:127], v[134:135]
	v_pk_mul_f32 v[150:151], v[128:129], v[136:137]
	v_cvt_pk_bf16_f32 v148, v142, v143
	v_lshlrev_b64 v[142:143], 15, v[138:139]
	s_waitcnt lgkmcnt(0)
	v_pk_mul_f32 v[152:153], v[122:123], v[130:131]
	v_pk_mul_f32 v[154:155], v[124:125], v[132:133]
	v_lshl_add_u64 v[142:143], s[34:35], 0, v[142:143]
	v_cvt_pk_bf16_f32 v149, v150, v151
	v_cvt_pk_bf16_f32 v150, v152, v153
	v_cvt_pk_bf16_f32 v151, v154, v155
	v_lshl_add_u64 v[142:143], v[142:143], 0, v[140:141]
	global_store_dwordx4 v[142:143], v[148:151], off nt
	v_pk_mul_f32 v[142:143], v[110:111], v[134:135]
	v_pk_mul_f32 v[152:153], v[106:107], v[130:131]
	v_cvt_pk_bf16_f32 v148, v142, v143
	v_add_u32_e32 v142, 16, v138
	v_ashrrev_i32_e32 v143, 31, v142
	v_lshlrev_b64 v[142:143], 15, v[142:143]
	v_pk_mul_f32 v[150:151], v[112:113], v[136:137]
	v_pk_mul_f32 v[154:155], v[108:109], v[132:133]
	v_lshl_add_u64 v[142:143], s[34:35], 0, v[142:143]
	v_cvt_pk_bf16_f32 v149, v150, v151
	v_cvt_pk_bf16_f32 v150, v152, v153
	v_cvt_pk_bf16_f32 v151, v154, v155
	v_lshl_add_u64 v[142:143], v[142:143], 0, v[140:141]
	global_store_dwordx4 v[142:143], v[148:151], off nt
	v_pk_mul_f32 v[142:143], v[94:95], v[134:135]
	v_pk_mul_f32 v[152:153], v[90:91], v[130:131]
	v_cvt_pk_bf16_f32 v148, v142, v143
	v_add_u32_e32 v142, 32, v138
	v_ashrrev_i32_e32 v143, 31, v142
	v_lshlrev_b64 v[142:143], 15, v[142:143]
	v_pk_mul_f32 v[150:151], v[96:97], v[136:137]
	v_pk_mul_f32 v[154:155], v[92:93], v[132:133]
	v_lshl_add_u64 v[142:143], s[34:35], 0, v[142:143]
	v_cvt_pk_bf16_f32 v149, v150, v151
	v_cvt_pk_bf16_f32 v150, v152, v153
	v_cvt_pk_bf16_f32 v151, v154, v155
	v_lshl_add_u64 v[142:143], v[142:143], 0, v[140:141]
	global_store_dwordx4 v[142:143], v[148:151], off nt
	v_pk_mul_f32 v[142:143], v[76:77], v[134:135]
	v_pk_mul_f32 v[152:153], v[72:73], v[130:131]
	v_cvt_pk_bf16_f32 v148, v142, v143
	v_add_u32_e32 v142, 48, v138
	v_ashrrev_i32_e32 v143, 31, v142
	v_lshlrev_b64 v[142:143], 15, v[142:143]
	v_pk_mul_f32 v[150:151], v[78:79], v[136:137]
	v_pk_mul_f32 v[154:155], v[74:75], v[132:133]
	v_lshl_add_u64 v[142:143], s[34:35], 0, v[142:143]
	v_cvt_pk_bf16_f32 v149, v150, v151
	v_cvt_pk_bf16_f32 v150, v152, v153
	v_cvt_pk_bf16_f32 v151, v154, v155
	v_lshl_add_u64 v[142:143], v[142:143], 0, v[140:141]
	global_store_dwordx4 v[142:143], v[148:151], off nt
	v_add_u32_e32 v142, 0x80, v138
	v_ashrrev_i32_e32 v143, 31, v142
	v_lshlrev_b64 v[142:143], 15, v[142:143]
	v_pk_mul_f32 v[148:149], v[60:61], v[134:135]
	v_pk_mul_f32 v[150:151], v[62:63], v[136:137]
	v_pk_mul_f32 v[152:153], v[56:57], v[130:131]
	v_pk_mul_f32 v[154:155], v[58:59], v[132:133]
	v_lshl_add_u64 v[142:143], s[34:35], 0, v[142:143]
	v_cvt_pk_bf16_f32 v148, v148, v149
	v_cvt_pk_bf16_f32 v149, v150, v151
	v_cvt_pk_bf16_f32 v150, v152, v153
	v_cvt_pk_bf16_f32 v151, v154, v155
	v_lshl_add_u64 v[142:143], v[142:143], 0, v[140:141]
	global_store_dwordx4 v[142:143], v[148:151], off nt
	v_pk_mul_f32 v[142:143], v[44:45], v[134:135]
	v_pk_mul_f32 v[152:153], v[40:41], v[130:131]
	v_cvt_pk_bf16_f32 v148, v142, v143
	v_add_u32_e32 v142, 0x90, v138
	v_ashrrev_i32_e32 v143, 31, v142
	v_lshlrev_b64 v[142:143], 15, v[142:143]
	v_pk_mul_f32 v[150:151], v[46:47], v[136:137]
	v_pk_mul_f32 v[154:155], v[42:43], v[132:133]
	v_lshl_add_u64 v[142:143], s[34:35], 0, v[142:143]
	v_cvt_pk_bf16_f32 v149, v150, v151
	v_cvt_pk_bf16_f32 v150, v152, v153
	v_cvt_pk_bf16_f32 v151, v154, v155
	v_lshl_add_u64 v[142:143], v[142:143], 0, v[140:141]
	global_store_dwordx4 v[142:143], v[148:151], off nt
	v_pk_mul_f32 v[142:143], v[28:29], v[134:135]
	v_pk_mul_f32 v[152:153], v[24:25], v[130:131]
	v_cvt_pk_bf16_f32 v148, v142, v143
	v_add_u32_e32 v142, 0xa0, v138
	v_ashrrev_i32_e32 v143, 31, v142
;     __device__ __forceinline__ void operator()(const f32x4 (&acc)[2][2][4][2], const Unit& u, int wr, int wc, int fr, int fq) const {
;     ...
;                 const int tok0 = u.pn * BM + bj * HALF + wc * 32 + 8 * fq, b = tok0 / seq, t = tok0 - b * seq;
;                 float rs[8];
; #pragma unroll
;                 for (int k = 0; k < 8; ++k) rs[k] = rt.tab[bj * 32 + 8 * fq + k];
; #pragma unroll
;                 for (int ai = 0; ai < 2; ++ai)
; #pragma unroll
;                     for (int m = 0; m < 4; ++m) {
;                         const int vc = ai * HALF + wr * 64 + m * 16 + fr;
;                         float o[8];
; #pragma unroll
;                         for (int n = 0; n < 2; ++n)
; #pragma unroll
;                             for (int j = 0; j < 4; ++j) o[n * 4 + j] = acc[ai][bj][m][n][j] * rs[n * 4 + j];
;                         *(u32x4*)(Vt + ((size_t)(b * 256 + vc)) * seq + t) = pack8(o);
;                     }
	v_lshlrev_b64 v[142:143], 15, v[142:143]
	v_pk_mul_f32 v[150:151], v[30:31], v[136:137]
	v_pk_mul_f32 v[154:155], v[26:27], v[132:133]
	v_lshl_add_u64 v[142:143], s[34:35], 0, v[142:143]
	v_cvt_pk_bf16_f32 v149, v150, v151
	v_cvt_pk_bf16_f32 v150, v152, v153
	v_cvt_pk_bf16_f32 v151, v154, v155
	v_lshl_add_u64 v[142:143], v[142:143], 0, v[140:141]
	v_pk_mul_f32 v[134:135], v[12:13], v[134:135]
	global_store_dwordx4 v[142:143], v[148:151], off nt
	v_pk_mul_f32 v[142:143], v[8:9], v[130:131]
	v_cvt_pk_bf16_f32 v130, v134, v135
	v_add_u32_e32 v134, 0xb0, v138
	v_ashrrev_i32_e32 v135, 31, v134
	v_lshlrev_b64 v[134:135], 15, v[134:135]
	v_pk_mul_f32 v[136:137], v[14:15], v[136:137]
	v_pk_mul_f32 v[148:149], v[10:11], v[132:133]
	v_lshl_add_u64 v[134:135], s[34:35], 0, v[134:135]
	v_cvt_pk_bf16_f32 v131, v136, v137
	v_cvt_pk_bf16_f32 v132, v142, v143
	v_cvt_pk_bf16_f32 v133, v148, v149
	v_lshl_add_u64 v[134:135], v[134:135], 0, v[140:141]
	global_store_dwordx4 v[134:135], v[130:133], off nt
	s_nop 1
	v_add_u32_e32 v130, 0x80, v145
	v_ashrrev_i32_e32 v131, 31, v130
	v_lshrrev_b32_e32 v131, 18, v131
	v_add_u32_e32 v131, v130, v131
	v_ashrrev_i32_e32 v132, 14, v131
	v_and_b32_e32 v131, 0xffffc000, v131
	v_sub_u32_e32 v142, v130, v131
	v_lshl_add_u32 v144, v132, 8, v144
	ds_read_b128 v[130:133], v146 offset:128
	ds_read_b128 v[134:137], v146 offset:144
	v_ashrrev_i32_e32 v145, 31, v144
	v_ashrrev_i32_e32 v143, 31, v142
	v_lshlrev_b64 v[142:143], 1, v[142:143]
	s_waitcnt lgkmcnt(1)
	v_pk_mul_f32 v[138:139], v[118:119], v[130:131]
	v_pk_mul_f32 v[140:141], v[120:121], v[132:133]
	s_waitcnt lgkmcnt(0)
	v_pk_mul_f32 v[146:147], v[114:115], v[134:135]
	v_cvt_pk_bf16_f32 v138, v138, v139
	v_cvt_pk_bf16_f32 v139, v140, v141
	v_cvt_pk_bf16_f32 v140, v146, v147
	v_lshlrev_b64 v[146:147], 15, v[144:145]
	v_pk_mul_f32 v[148:149], v[116:117], v[136:137]
	v_lshl_add_u64 v[146:147], s[34:35], 0, v[146:147]
	v_cvt_pk_bf16_f32 v141, v148, v149
	v_lshl_add_u64 v[146:147], v[146:147], 0, v[142:143]
	global_store_dwordx4 v[146:147], v[138:141], off nt
	v_pk_mul_f32 v[146:147], v[98:99], v[134:135]
	v_pk_mul_f32 v[148:149], v[100:101], v[136:137]
	v_pk_mul_f32 v[138:139], v[102:103], v[130:131]
	v_pk_mul_f32 v[140:141], v[104:105], v[132:133]
	v_cvt_pk_bf16_f32 v138, v138, v139
	v_cvt_pk_bf16_f32 v139, v140, v141
	v_cvt_pk_bf16_f32 v140, v146, v147
	v_add_u32_e32 v146, 16, v144
	v_ashrrev_i32_e32 v147, 31, v146
	v_lshlrev_b64 v[146:147], 15, v[146:147]
	v_lshl_add_u64 v[146:147], s[34:35], 0, v[146:147]
	v_cvt_pk_bf16_f32 v141, v148, v149
	v_lshl_add_u64 v[146:147], v[146:147], 0, v[142:143]
	global_store_dwordx4 v[146:147], v[138:141], off nt
	v_pk_mul_f32 v[146:147], v[82:83], v[134:135]
	v_pk_mul_f32 v[148:149], v[84:85], v[136:137]
	v_pk_mul_f32 v[138:139], v[86:87], v[130:131]
	v_pk_mul_f32 v[140:141], v[88:89], v[132:133]
	v_cvt_pk_bf16_f32 v138, v138, v139
	v_cvt_pk_bf16_f32 v139, v140, v141
	v_cvt_pk_bf16_f32 v140, v146, v147
	v_add_u32_e32 v146, 32, v144
	v_ashrrev_i32_e32 v147, 31, v146
	v_lshlrev_b64 v[146:147], 15, v[146:147]
	v_lshl_add_u64 v[146:147], s[34:35], 0, v[146:147]
	v_cvt_pk_bf16_f32 v141, v148, v149
	v_lshl_add_u64 v[146:147], v[146:147], 0, v[142:143]
	global_store_dwordx4 v[146:147], v[138:141], off nt
	v_pk_mul_f32 v[146:147], v[64:65], v[134:135]
	v_pk_mul_f32 v[148:149], v[66:67], v[136:137]
	v_pk_mul_f32 v[138:139], v[68:69], v[130:131]
	v_pk_mul_f32 v[140:141], v[70:71], v[132:133]
	v_cvt_pk_bf16_f32 v138, v138, v139
	v_cvt_pk_bf16_f32 v139, v140, v141
	v_cvt_pk_bf16_f32 v140, v146, v147
	v_add_u32_e32 v146, 48, v144
	v_ashrrev_i32_e32 v147, 31, v146
	v_lshlrev_b64 v[146:147], 15, v[146:147]
	v_lshl_add_u64 v[146:147], s[34:35], 0, v[146:147]
	v_cvt_pk_bf16_f32 v141, v148, v149
	v_lshl_add_u64 v[146:147], v[146:147], 0, v[142:143]
	global_store_dwordx4 v[146:147], v[138:141], off nt
	v_add_u32_e32 v146, 0x80, v144
	v_ashrrev_i32_e32 v147, 31, v146
	v_lshlrev_b64 v[146:147], 15, v[146:147]
	v_pk_mul_f32 v[138:139], v[52:53], v[130:131]
	v_pk_mul_f32 v[140:141], v[54:55], v[132:133]
	v_pk_mul_f32 v[148:149], v[48:49], v[134:135]
	v_pk_mul_f32 v[150:151], v[50:51], v[136:137]
	v_lshl_add_u64 v[146:147], s[34:35], 0, v[146:147]
	v_cvt_pk_bf16_f32 v138, v138, v139
	v_cvt_pk_bf16_f32 v139, v140, v141
	v_cvt_pk_bf16_f32 v140, v148, v149
	v_cvt_pk_bf16_f32 v141, v150, v151
	v_lshl_add_u64 v[146:147], v[146:147], 0, v[142:143]
	global_store_dwordx4 v[146:147], v[138:141], off nt
	v_pk_mul_f32 v[146:147], v[32:33], v[134:135]
	v_pk_mul_f32 v[148:149], v[34:35], v[136:137]
	v_pk_mul_f32 v[138:139], v[36:37], v[130:131]
	v_pk_mul_f32 v[140:141], v[38:39], v[132:133]
	v_cvt_pk_bf16_f32 v138, v138, v139
	v_cvt_pk_bf16_f32 v139, v140, v141
	v_cvt_pk_bf16_f32 v140, v146, v147
	v_add_u32_e32 v146, 0x90, v144
	v_ashrrev_i32_e32 v147, 31, v146
	v_lshlrev_b64 v[146:147], 15, v[146:147]
	v_lshl_add_u64 v[146:147], s[34:35], 0, v[146:147]
	v_cvt_pk_bf16_f32 v141, v148, v149
	v_lshl_add_u64 v[146:147], v[146:147], 0, v[142:143]
	global_store_dwordx4 v[146:147], v[138:141], off nt
	v_pk_mul_f32 v[146:147], v[16:17], v[134:135]
	v_pk_mul_f32 v[134:135], v[0:1], v[134:135]
	v_pk_mul_f32 v[138:139], v[20:21], v[130:131]
	v_pk_mul_f32 v[140:141], v[22:23], v[132:133]
	v_pk_mul_f32 v[130:131], v[4:5], v[130:131]
	v_pk_mul_f32 v[132:133], v[6:7], v[132:133]
	v_cvt_pk_bf16_f32 v138, v138, v139
	v_cvt_pk_bf16_f32 v139, v140, v141
	v_cvt_pk_bf16_f32 v140, v146, v147
	v_add_u32_e32 v146, 0xa0, v144
	v_cvt_pk_bf16_f32 v130, v130, v131
	v_cvt_pk_bf16_f32 v131, v132, v133
	v_cvt_pk_bf16_f32 v132, v134, v135
	v_add_u32_e32 v134, 0xb0, v144
	v_ashrrev_i32_e32 v147, 31, v146
	v_ashrrev_i32_e32 v135, 31, v134
	v_lshlrev_b64 v[146:147], 15, v[146:147]
	v_lshlrev_b64 v[134:135], 15, v[134:135]
	v_pk_mul_f32 v[148:149], v[18:19], v[136:137]
	v_lshl_add_u64 v[146:147], s[34:35], 0, v[146:147]
	v_pk_mul_f32 v[136:137], v[2:3], v[136:137]
	v_lshl_add_u64 v[134:135], s[34:35], 0, v[134:135]
	v_cvt_pk_bf16_f32 v141, v148, v149
	v_lshl_add_u64 v[146:147], v[146:147], 0, v[142:143]
	v_cvt_pk_bf16_f32 v133, v136, v137
	v_lshl_add_u64 v[134:135], v[134:135], 0, v[142:143]
	global_store_dwordx4 v[146:147], v[138:141], off nt
	global_store_dwordx4 v[134:135], v[130:133], off nt
	s_mov_b32 s5, -1
	s_cbranch_execz .LBB0_166
	s_mov_b32 s66, s5
	s_andn2_b64 vcc, exec, s[42:43]
	s_mov_b64 s[4:5], -1
	s_cbranch_vccnz .LBB0_152
	s_branch .LBB0_201

;     __device__ __forceinline__ void operator()(const f32x4 (&acc)[2][2][4][2], const Unit& u, int wr, int wc, int fr, int fq) const {
;     ...
;             for (int it = 0; it < 8; ++it) {
;                 const int ai = it >> 2, m = it & 3;
;                 const int row = row0 + ai * HALF + m * 16;
;                 float rs = rt.get(ai, m, fr); if (isq) rs *= QSCALE_F;
;                 const f32x4 t0 = tn[0], t1 = tn[1], t2 = tn[2], t3 = tn[3];
;                 if (it < 7) { const int nrow = row0 + ((it + 1) >> 2) * HALF + ((it + 1) & 3) * 16; const f32x4* cp = (const f32x4*)(cs + (size_t)nrow * 64 + 16 * fq); tn[0] = cp[0]; tn[1] = cp[1]; tn[2] = cp[2]; tn[3] = cp[3]; }
;                 const float cc[8] = {t0[0], t0[2], t1[0], t1[2], t2[0], t2[2], t3[0], t3[2]};
;                 const float sn[8] = {t0[1], t0[3], t1[1], t1[3], t2[1], t2[3], t3[1], t3[3]};
;                 float o1[8], o2[8];
; #pragma unroll
;                 for (int n = 0; n < 2; ++n)
; #pragma unroll
;                     for (int j = 0; j < 4; ++j) {
;                         const int k = n * 4 + j;
;                         const float x1 = acc[ai][0][m][n][j] * rs, x2 = acc[ai][1][m][n][j] * rs;
;                         o1[k] = x1 * cc[k] - x2 * sn[k]; o2[k] = x2 * cc[k] + x1 * sn[k];
;                     }
;                 bf16_t* dst;
;                 if (isq) dst = Q + (size_t)row * 1024 + u.pn * 256 + wc * 64 + 8 * fq;
;                 else { const int b = row / seq, t = row - b * seq; dst = Kb + ((size_t)(b * 4 + wc) * seq + t) * 64 + 8 * fq; }
;                 *(u32x4*)dst = pack8(o1); *(u32x4*)(dst + 32) = pack8(o2);
.LBB0_172:
	s_waitcnt lgkmcnt(0)
	v_mul_f32_e32 v193, 0x3e38aa3b, v208
	v_cndmask_b32_e64 v208, v208, v193, s[6:7]
	v_pk_mul_f32 v[118:119], v[118:119], v[208:209] op_sel_hi:[1,0]
	s_waitcnt vmcnt(0)
	v_mov_b32_e32 v210, v158
	v_mov_b32_e32 v211, v160
	v_mov_b32_e32 v160, v159
	v_pk_mul_f32 v[126:127], v[126:127], v[208:209] op_sel_hi:[1,0]
	v_pk_mul_f32 v[212:213], v[210:211], v[118:119]
	v_pk_mul_f32 v[118:119], v[160:161], v[118:119]
	v_pk_fma_f32 v[158:159], v[160:161], v[126:127], v[212:213]
	v_pk_fma_f32 v[118:119], v[210:211], v[126:127], v[118:119] neg_lo:[0,0,1] neg_hi:[0,0,1]
	v_pk_mul_f32 v[126:127], v[128:129], v[208:209] op_sel_hi:[1,0]
	v_pk_mul_f32 v[120:121], v[120:121], v[208:209] op_sel_hi:[1,0]
	v_mov_b32_e32 v128, v154
	v_mov_b32_e32 v129, v156
	v_mov_b32_e32 v156, v155
	v_pk_mul_f32 v[160:161], v[128:129], v[120:121]
	v_pk_mul_f32 v[120:121], v[156:157], v[120:121]
	v_pk_fma_f32 v[154:155], v[156:157], v[126:127], v[160:161]
	v_pk_fma_f32 v[120:121], v[128:129], v[126:127], v[120:121] neg_lo:[0,0,1] neg_hi:[0,0,1]
	v_pk_mul_f32 v[114:115], v[114:115], v[208:209] op_sel_hi:[1,0]
	v_mov_b32_e32 v126, v150
	v_mov_b32_e32 v127, v152
	v_mov_b32_e32 v152, v151
	v_pk_mul_f32 v[122:123], v[122:123], v[208:209] op_sel_hi:[1,0]
	v_pk_mul_f32 v[128:129], v[126:127], v[114:115]
	v_pk_mul_f32 v[114:115], v[152:153], v[114:115]
	v_pk_fma_f32 v[128:129], v[152:153], v[122:123], v[128:129]
	v_pk_fma_f32 v[122:123], v[126:127], v[122:123], v[114:115] neg_lo:[0,0,1] neg_hi:[0,0,1]
	v_pk_mul_f32 v[114:115], v[124:125], v[208:209] op_sel_hi:[1,0]
	v_pk_mul_f32 v[116:117], v[116:117], v[208:209] op_sel_hi:[1,0]
	v_mov_b32_e32 v124, v146
	v_mov_b32_e32 v125, v148
	v_mov_b32_e32 v148, v147
	v_lshlrev_b32_e32 v190, 3, v190
	v_pk_mul_f32 v[126:127], v[124:125], v[116:117]
	v_pk_mul_f32 v[116:117], v[148:149], v[116:117]
	v_ashrrev_i32_e32 v191, 31, v190
	v_pk_fma_f32 v[124:125], v[124:125], v[114:115], v[116:117] neg_lo:[0,0,1] neg_hi:[0,0,1]
	v_pk_fma_f32 v[126:127], v[148:149], v[114:115], v[126:127]
	v_lshl_add_u64 v[146:147], v[190:191], 1, v[196:197]
	v_cvt_pk_bf16_f32 v114, v118, v119
	v_cvt_pk_bf16_f32 v115, v120, v121
	v_cvt_pk_bf16_f32 v116, v122, v123
	v_cvt_pk_bf16_f32 v117, v124, v125
	global_store_dwordx4 v[146:147], v[114:117], off nt
	v_cndmask_b32_e64 v148, 0, 1, s[48:49]
	v_cmp_ne_u32_e64 s[4:5], 1, v148
	v_cvt_pk_bf16_f32 v114, v158, v159
	v_cvt_pk_bf16_f32 v115, v154, v155
	v_cvt_pk_bf16_f32 v116, v128, v129
	v_cvt_pk_bf16_f32 v117, v126, v127
	global_store_dwordx4 v[146:147], v[114:117], off offset:64 nt
	v_add_u32_e32 v146, 32, v192
	v_ashrrev_i32_e32 v147, 31, v146
	v_lshlrev_b64 v[114:115], 8, v[146:147]
	v_lshl_add_u64 v[114:115], s[22:23], 0, v[114:115]
	v_lshl_add_u64 v[126:127], v[188:189], 2, v[114:115]
	global_load_dwordx4 v[114:117], v[126:127], off offset:48
	global_load_dwordx4 v[118:121], v[126:127], off offset:32
	global_load_dwordx4 v[122:125], v[126:127], off offset:16
	s_nop 0
	global_load_dwordx4 v[126:129], v[126:127], off
	ds_read_b32 v150, v201 offset:64
	s_andn2_b64 vcc, exec, s[48:49]
	s_mov_b64 s[48:49], -1
	s_cbranch_vccnz .LBB0_174
	v_ashrrev_i32_e32 v148, 31, v194
	v_lshrrev_b32_e32 v148, 18, v148
	v_add_u32_e32 v148, v194, v148
	v_ashrrev_i32_e32 v149, 14, v148
	v_and_b32_e32 v148, 0xffffc000, v148
	v_lshl_or_b32 v152, v149, 2, s58
	v_sub_u32_e32 v148, v194, v148
	v_ashrrev_i32_e32 v153, 31, v152
	v_ashrrev_i32_e32 v149, 31, v148
	v_lshlrev_b64 v[152:153], 21, v[152:153]
	v_lshlrev_b64 v[148:149], 7, v[148:149]
	v_lshl_add_u64 v[152:153], s[0:1], 0, v[152:153]
	v_lshl_add_u64 v[148:149], v[152:153], 0, v[148:149]
	s_mov_b64 s[48:49], 0

;     __device__ __forceinline__ void operator()(const f32x4 (&acc)[2][2][4][2], const Unit& u, int wr, int wc, int fr, int fq) const {
;     ...
;             for (int it = 0; it < 8; ++it) {
;                 const int ai = it >> 2, m = it & 3;
;                 const int row = row0 + ai * HALF + m * 16;
;                 float rs = rt.get(ai, m, fr); if (isq) rs *= QSCALE_F;
;                 const f32x4 t0 = tn[0], t1 = tn[1], t2 = tn[2], t3 = tn[3];
;                 if (it < 7) { const int nrow = row0 + ((it + 1) >> 2) * HALF + ((it + 1) & 3) * 16; const f32x4* cp = (const f32x4*)(cs + (size_t)nrow * 64 + 16 * fq); tn[0] = cp[0]; tn[1] = cp[1]; tn[2] = cp[2]; tn[3] = cp[3]; }
;                 const float cc[8] = {t0[0], t0[2], t1[0], t1[2], t2[0], t2[2], t3[0], t3[2]};
;                 const float sn[8] = {t0[1], t0[3], t1[1], t1[3], t2[1], t2[3], t3[1], t3[3]};
;                 float o1[8], o2[8];
; #pragma unroll
;                 for (int n = 0; n < 2; ++n)
; #pragma unroll
;                     for (int j = 0; j < 4; ++j) {
;                         const int k = n * 4 + j;
;                         const float x1 = acc[ai][0][m][n][j] * rs, x2 = acc[ai][1][m][n][j] * rs;
;                         o1[k] = x1 * cc[k] - x2 * sn[k]; o2[k] = x2 * cc[k] + x1 * sn[k];
;                     }
;                 bf16_t* dst;
;                 if (isq) dst = Q + (size_t)row * 1024 + u.pn * 256 + wc * 64 + 8 * fq;
;                 else { const int b = row / seq, t = row - b * seq; dst = Kb + ((size_t)(b * 4 + wc) * seq + t) * 64 + 8 * fq; }
;                 *(u32x4*)dst = pack8(o1); *(u32x4*)(dst + 32) = pack8(o2);
.LBB0_176:
	s_waitcnt lgkmcnt(0)
	v_mul_f32_e32 v151, 0x3e38aa3b, v150
	v_cndmask_b32_e64 v150, v150, v151, s[6:7]
	v_pk_mul_f32 v[102:103], v[102:103], v[150:151] op_sel_hi:[1,0]
	v_mov_b32_e32 v152, v142
	v_mov_b32_e32 v153, v144
	v_mov_b32_e32 v144, v143
	v_pk_mul_f32 v[110:111], v[110:111], v[150:151] op_sel_hi:[1,0]
	v_pk_mul_f32 v[154:155], v[152:153], v[102:103]
	v_pk_mul_f32 v[102:103], v[144:145], v[102:103]
	v_pk_fma_f32 v[142:143], v[144:145], v[110:111], v[154:155]
	v_pk_fma_f32 v[102:103], v[152:153], v[110:111], v[102:103] neg_lo:[0,0,1] neg_hi:[0,0,1]
	v_pk_mul_f32 v[110:111], v[112:113], v[150:151] op_sel_hi:[1,0]
	v_pk_mul_f32 v[104:105], v[104:105], v[150:151] op_sel_hi:[1,0]
	v_mov_b32_e32 v112, v138
	v_mov_b32_e32 v113, v140
	v_mov_b32_e32 v140, v139
	v_pk_mul_f32 v[144:145], v[112:113], v[104:105]
	v_pk_mul_f32 v[104:105], v[140:141], v[104:105]
	v_pk_fma_f32 v[138:139], v[140:141], v[110:111], v[144:145]
	v_pk_fma_f32 v[104:105], v[112:113], v[110:111], v[104:105] neg_lo:[0,0,1] neg_hi:[0,0,1]
	v_pk_mul_f32 v[98:99], v[98:99], v[150:151] op_sel_hi:[1,0]
	v_mov_b32_e32 v110, v134
	v_mov_b32_e32 v111, v136
	v_mov_b32_e32 v136, v135
	v_pk_mul_f32 v[106:107], v[106:107], v[150:151] op_sel_hi:[1,0]
	v_pk_mul_f32 v[112:113], v[110:111], v[98:99]
	v_pk_mul_f32 v[98:99], v[136:137], v[98:99]
	v_pk_fma_f32 v[112:113], v[136:137], v[106:107], v[112:113]
	v_pk_fma_f32 v[106:107], v[110:111], v[106:107], v[98:99] neg_lo:[0,0,1] neg_hi:[0,0,1]
	v_pk_mul_f32 v[98:99], v[108:109], v[150:151] op_sel_hi:[1,0]
	v_pk_mul_f32 v[100:101], v[100:101], v[150:151] op_sel_hi:[1,0]
	v_mov_b32_e32 v108, v130
	v_mov_b32_e32 v109, v132
	v_mov_b32_e32 v132, v131
	v_pk_mul_f32 v[110:111], v[108:109], v[100:101]
	v_pk_mul_f32 v[100:101], v[132:133], v[100:101]
	v_pk_fma_f32 v[110:111], v[132:133], v[98:99], v[110:111]
	v_pk_fma_f32 v[108:109], v[108:109], v[98:99], v[100:101] neg_lo:[0,0,1] neg_hi:[0,0,1]
	v_lshl_add_u64 v[130:131], v[190:191], 1, v[148:149]
	v_cvt_pk_bf16_f32 v98, v102, v103
	v_cvt_pk_bf16_f32 v99, v104, v105
	v_cvt_pk_bf16_f32 v100, v106, v107
	v_cvt_pk_bf16_f32 v101, v108, v109
	global_store_dwordx4 v[130:131], v[98:101], off nt
	s_and_b64 vcc, exec, s[4:5]
	s_mov_b64 s[48:49], -1
	v_cvt_pk_bf16_f32 v98, v142, v143
	v_cvt_pk_bf16_f32 v99, v138, v139
	v_cvt_pk_bf16_f32 v100, v112, v113
	v_cvt_pk_bf16_f32 v101, v110, v111
	global_store_dwordx4 v[130:131], v[98:101], off offset:64 nt
	v_add_u32_e32 v130, 48, v192
	v_ashrrev_i32_e32 v131, 31, v130
	v_lshlrev_b64 v[98:99], 8, v[130:131]
	v_lshl_add_u64 v[98:99], s[22:23], 0, v[98:99]
	v_lshl_add_u64 v[110:111], v[188:189], 2, v[98:99]
	global_load_dwordx4 v[98:101], v[110:111], off offset:48
	global_load_dwordx4 v[102:105], v[110:111], off offset:32
	global_load_dwordx4 v[106:109], v[110:111], off offset:16
	s_nop 0
	global_load_dwordx4 v[110:113], v[110:111], off
	ds_read_b32 v134, v201 offset:128
	s_cbranch_vccnz .LBB0_178
	v_ashrrev_i32_e32 v132, 31, v146
	v_lshrrev_b32_e32 v132, 18, v132
	v_add_u32_e32 v132, v146, v132
	v_ashrrev_i32_e32 v133, 14, v132
	v_and_b32_e32 v132, 0xffffc000, v132
	v_lshl_or_b32 v136, v133, 2, s58
	v_sub_u32_e32 v132, v146, v132
	v_ashrrev_i32_e32 v137, 31, v136
	v_ashrrev_i32_e32 v133, 31, v132
	v_lshlrev_b64 v[136:137], 21, v[136:137]
	v_lshlrev_b64 v[132:133], 7, v[132:133]
	v_lshl_add_u64 v[136:137], s[0:1], 0, v[136:137]
	v_lshl_add_u64 v[132:133], v[136:137], 0, v[132:133]
	s_mov_b64 s[48:49], 0

;     __device__ __forceinline__ void operator()(const f32x4 (&acc)[2][2][4][2], const Unit& u, int wr, int wc, int fr, int fq) const {
;     ...
;             for (int it = 0; it < 8; ++it) {
;                 const int ai = it >> 2, m = it & 3;
;                 const int row = row0 + ai * HALF + m * 16;
;                 float rs = rt.get(ai, m, fr); if (isq) rs *= QSCALE_F;
;                 const f32x4 t0 = tn[0], t1 = tn[1], t2 = tn[2], t3 = tn[3];
;                 if (it < 7) { const int nrow = row0 + ((it + 1) >> 2) * HALF + ((it + 1) & 3) * 16; const f32x4* cp = (const f32x4*)(cs + (size_t)nrow * 64 + 16 * fq); tn[0] = cp[0]; tn[1] = cp[1]; tn[2] = cp[2]; tn[3] = cp[3]; }
;                 const float cc[8] = {t0[0], t0[2], t1[0], t1[2], t2[0], t2[2], t3[0], t3[2]};
;                 const float sn[8] = {t0[1], t0[3], t1[1], t1[3], t2[1], t2[3], t3[1], t3[3]};
;                 float o1[8], o2[8];
; #pragma unroll
;                 for (int n = 0; n < 2; ++n)
; #pragma unroll
;                     for (int j = 0; j < 4; ++j) {
;                         const int k = n * 4 + j;
;                         const float x1 = acc[ai][0][m][n][j] * rs, x2 = acc[ai][1][m][n][j] * rs;
;                         o1[k] = x1 * cc[k] - x2 * sn[k]; o2[k] = x2 * cc[k] + x1 * sn[k];
;                     }
;                 bf16_t* dst;
;                 if (isq) dst = Q + (size_t)row * 1024 + u.pn * 256 + wc * 64 + 8 * fq;
;                 else { const int b = row / seq, t = row - b * seq; dst = Kb + ((size_t)(b * 4 + wc) * seq + t) * 64 + 8 * fq; }
;                 *(u32x4*)dst = pack8(o1); *(u32x4*)(dst + 32) = pack8(o2);
.LBB0_180:
	s_waitcnt lgkmcnt(0)
	v_mul_f32_e32 v135, 0x3e38aa3b, v134
	v_cndmask_b32_e64 v134, v134, v135, s[6:7]
	v_pk_mul_f32 v[86:87], v[86:87], v[134:135] op_sel_hi:[1,0]
	s_waitcnt vmcnt(6)
	v_mov_b32_e32 v136, v126
	v_mov_b32_e32 v137, v128
	v_mov_b32_e32 v128, v127
	v_pk_mul_f32 v[94:95], v[94:95], v[134:135] op_sel_hi:[1,0]
	v_pk_mul_f32 v[138:139], v[136:137], v[86:87]
	v_pk_mul_f32 v[86:87], v[128:129], v[86:87]
	v_pk_fma_f32 v[126:127], v[128:129], v[94:95], v[138:139]
	v_pk_fma_f32 v[86:87], v[136:137], v[94:95], v[86:87] neg_lo:[0,0,1] neg_hi:[0,0,1]
	v_pk_mul_f32 v[94:95], v[96:97], v[134:135] op_sel_hi:[1,0]
	v_pk_mul_f32 v[88:89], v[88:89], v[134:135] op_sel_hi:[1,0]
	v_mov_b32_e32 v96, v122
	v_mov_b32_e32 v97, v124
	v_mov_b32_e32 v124, v123
	v_pk_mul_f32 v[128:129], v[96:97], v[88:89]
	v_pk_mul_f32 v[88:89], v[124:125], v[88:89]
	v_pk_fma_f32 v[122:123], v[124:125], v[94:95], v[128:129]
	v_pk_fma_f32 v[88:89], v[96:97], v[94:95], v[88:89] neg_lo:[0,0,1] neg_hi:[0,0,1]
	v_pk_mul_f32 v[82:83], v[82:83], v[134:135] op_sel_hi:[1,0]
	v_mov_b32_e32 v94, v118
	v_mov_b32_e32 v95, v120
	v_mov_b32_e32 v120, v119
	v_pk_mul_f32 v[90:91], v[90:91], v[134:135] op_sel_hi:[1,0]
	v_pk_mul_f32 v[96:97], v[94:95], v[82:83]
	v_pk_mul_f32 v[82:83], v[120:121], v[82:83]
	v_pk_fma_f32 v[96:97], v[120:121], v[90:91], v[96:97]
	v_pk_fma_f32 v[90:91], v[94:95], v[90:91], v[82:83] neg_lo:[0,0,1] neg_hi:[0,0,1]
	v_pk_mul_f32 v[82:83], v[92:93], v[134:135] op_sel_hi:[1,0]
	v_pk_mul_f32 v[84:85], v[84:85], v[134:135] op_sel_hi:[1,0]
	v_mov_b32_e32 v92, v114
	v_mov_b32_e32 v93, v116
	v_mov_b32_e32 v116, v115
	v_pk_mul_f32 v[94:95], v[92:93], v[84:85]
	v_pk_mul_f32 v[84:85], v[116:117], v[84:85]
	v_pk_fma_f32 v[94:95], v[116:117], v[82:83], v[94:95]
	v_pk_fma_f32 v[92:93], v[92:93], v[82:83], v[84:85] neg_lo:[0,0,1] neg_hi:[0,0,1]
	v_lshl_add_u64 v[114:115], v[190:191], 1, v[132:133]
	v_cvt_pk_bf16_f32 v82, v86, v87
	v_cvt_pk_bf16_f32 v83, v88, v89
	v_cvt_pk_bf16_f32 v84, v90, v91
	v_cvt_pk_bf16_f32 v85, v92, v93
	global_store_dwordx4 v[114:115], v[82:85], off nt
	s_and_b64 vcc, exec, s[4:5]
	s_mov_b64 s[48:49], -1
	v_cvt_pk_bf16_f32 v82, v126, v127
	v_cvt_pk_bf16_f32 v83, v122, v123
	v_cvt_pk_bf16_f32 v84, v96, v97
	v_cvt_pk_bf16_f32 v85, v94, v95
	global_store_dwordx4 v[114:115], v[82:85], off offset:64 nt
	v_add_u32_e32 v114, 0x80, v192
	v_ashrrev_i32_e32 v115, 31, v114
	v_lshlrev_b64 v[82:83], 8, v[114:115]
	v_lshl_add_u64 v[82:83], s[22:23], 0, v[82:83]
	v_lshl_add_u64 v[94:95], v[188:189], 2, v[82:83]
	global_load_dwordx4 v[82:85], v[94:95], off offset:48
	global_load_dwordx4 v[86:89], v[94:95], off offset:32
	global_load_dwordx4 v[90:93], v[94:95], off offset:16
	s_nop 0
	global_load_dwordx4 v[94:97], v[94:95], off
	ds_read_b32 v118, v201 offset:192
	s_cbranch_vccnz .LBB0_182
	v_ashrrev_i32_e32 v116, 31, v130
	v_lshrrev_b32_e32 v116, 18, v116
	v_add_u32_e32 v116, v130, v116
	v_ashrrev_i32_e32 v117, 14, v116
	v_and_b32_e32 v116, 0xffffc000, v116
	v_lshl_or_b32 v120, v117, 2, s58
	v_sub_u32_e32 v116, v130, v116
	v_ashrrev_i32_e32 v121, 31, v120
	v_ashrrev_i32_e32 v117, 31, v116
	v_lshlrev_b64 v[120:121], 21, v[120:121]
	v_lshlrev_b64 v[116:117], 7, v[116:117]
	v_lshl_add_u64 v[120:121], s[0:1], 0, v[120:121]
	v_lshl_add_u64 v[116:117], v[120:121], 0, v[116:117]
	s_mov_b64 s[48:49], 0

;     __device__ __forceinline__ void operator()(const f32x4 (&acc)[2][2][4][2], const Unit& u, int wr, int wc, int fr, int fq) const {
;     ...
;             for (int it = 0; it < 8; ++it) {
;                 const int ai = it >> 2, m = it & 3;
;                 const int row = row0 + ai * HALF + m * 16;
;                 float rs = rt.get(ai, m, fr); if (isq) rs *= QSCALE_F;
;                 const f32x4 t0 = tn[0], t1 = tn[1], t2 = tn[2], t3 = tn[3];
;                 if (it < 7) { const int nrow = row0 + ((it + 1) >> 2) * HALF + ((it + 1) & 3) * 16; const f32x4* cp = (const f32x4*)(cs + (size_t)nrow * 64 + 16 * fq); tn[0] = cp[0]; tn[1] = cp[1]; tn[2] = cp[2]; tn[3] = cp[3]; }
;                 const float cc[8] = {t0[0], t0[2], t1[0], t1[2], t2[0], t2[2], t3[0], t3[2]};
;                 const float sn[8] = {t0[1], t0[3], t1[1], t1[3], t2[1], t2[3], t3[1], t3[3]};
;                 float o1[8], o2[8];
; #pragma unroll
;                 for (int n = 0; n < 2; ++n)
; #pragma unroll
;                     for (int j = 0; j < 4; ++j) {
;                         const int k = n * 4 + j;
;                         const float x1 = acc[ai][0][m][n][j] * rs, x2 = acc[ai][1][m][n][j] * rs;
;                         o1[k] = x1 * cc[k] - x2 * sn[k]; o2[k] = x2 * cc[k] + x1 * sn[k];
;                     }
;                 bf16_t* dst;
;                 if (isq) dst = Q + (size_t)row * 1024 + u.pn * 256 + wc * 64 + 8 * fq;
;                 else { const int b = row / seq, t = row - b * seq; dst = Kb + ((size_t)(b * 4 + wc) * seq + t) * 64 + 8 * fq; }
;                 *(u32x4*)dst = pack8(o1); *(u32x4*)(dst + 32) = pack8(o2);
.LBB0_184:
	s_waitcnt lgkmcnt(0)
	v_mul_f32_e32 v119, 0x3e38aa3b, v118
	v_cndmask_b32_e64 v118, v118, v119, s[6:7]
	v_pk_mul_f32 v[68:69], v[68:69], v[118:119] op_sel_hi:[1,0]
	s_waitcnt vmcnt(6)
	v_mov_b32_e32 v120, v110
	v_mov_b32_e32 v121, v112
	v_mov_b32_e32 v112, v111
	v_pk_mul_f32 v[76:77], v[76:77], v[118:119] op_sel_hi:[1,0]
	v_pk_mul_f32 v[122:123], v[120:121], v[68:69]
	v_pk_mul_f32 v[68:69], v[112:113], v[68:69]
	v_pk_fma_f32 v[110:111], v[112:113], v[76:77], v[122:123]
	v_pk_fma_f32 v[68:69], v[120:121], v[76:77], v[68:69] neg_lo:[0,0,1] neg_hi:[0,0,1]
	v_pk_mul_f32 v[76:77], v[78:79], v[118:119] op_sel_hi:[1,0]
	v_pk_mul_f32 v[70:71], v[70:71], v[118:119] op_sel_hi:[1,0]
	v_mov_b32_e32 v78, v106
	v_mov_b32_e32 v79, v108
	v_mov_b32_e32 v108, v107
	v_pk_mul_f32 v[112:113], v[78:79], v[70:71]
	v_pk_mul_f32 v[70:71], v[108:109], v[70:71]
	v_pk_fma_f32 v[106:107], v[108:109], v[76:77], v[112:113]
	v_pk_fma_f32 v[70:71], v[78:79], v[76:77], v[70:71] neg_lo:[0,0,1] neg_hi:[0,0,1]
	v_pk_mul_f32 v[64:65], v[64:65], v[118:119] op_sel_hi:[1,0]
	v_mov_b32_e32 v76, v102
	v_mov_b32_e32 v77, v104
	v_mov_b32_e32 v104, v103
	v_pk_mul_f32 v[72:73], v[72:73], v[118:119] op_sel_hi:[1,0]
	v_pk_mul_f32 v[78:79], v[76:77], v[64:65]
	v_pk_mul_f32 v[64:65], v[104:105], v[64:65]
	v_pk_fma_f32 v[78:79], v[104:105], v[72:73], v[78:79]
	v_pk_fma_f32 v[72:73], v[76:77], v[72:73], v[64:65] neg_lo:[0,0,1] neg_hi:[0,0,1]
	v_pk_mul_f32 v[64:65], v[74:75], v[118:119] op_sel_hi:[1,0]
	v_pk_mul_f32 v[66:67], v[66:67], v[118:119] op_sel_hi:[1,0]
	v_mov_b32_e32 v74, v98
	v_mov_b32_e32 v75, v100
	v_mov_b32_e32 v100, v99
	v_pk_mul_f32 v[76:77], v[74:75], v[66:67]
	v_pk_mul_f32 v[66:67], v[100:101], v[66:67]
	v_pk_fma_f32 v[76:77], v[100:101], v[64:65], v[76:77]
	v_pk_fma_f32 v[74:75], v[74:75], v[64:65], v[66:67] neg_lo:[0,0,1] neg_hi:[0,0,1]
	v_lshl_add_u64 v[98:99], v[190:191], 1, v[116:117]
	v_cvt_pk_bf16_f32 v64, v68, v69
	v_cvt_pk_bf16_f32 v65, v70, v71
	v_cvt_pk_bf16_f32 v66, v72, v73
	v_cvt_pk_bf16_f32 v67, v74, v75
	global_store_dwordx4 v[98:99], v[64:67], off nt
	s_and_b64 vcc, exec, s[4:5]
	s_mov_b64 s[48:49], -1
	v_cvt_pk_bf16_f32 v64, v110, v111
	v_cvt_pk_bf16_f32 v65, v106, v107
	v_cvt_pk_bf16_f32 v66, v78, v79
	v_cvt_pk_bf16_f32 v67, v76, v77
	global_store_dwordx4 v[98:99], v[64:67], off offset:64 nt
	v_add_u32_e32 v98, 0x90, v192
	v_ashrrev_i32_e32 v99, 31, v98
	v_lshlrev_b64 v[64:65], 8, v[98:99]
	v_lshl_add_u64 v[64:65], s[22:23], 0, v[64:65]
	v_lshl_add_u64 v[76:77], v[188:189], 2, v[64:65]
	global_load_dwordx4 v[64:67], v[76:77], off offset:48
	global_load_dwordx4 v[68:71], v[76:77], off offset:32
	global_load_dwordx4 v[72:75], v[76:77], off offset:16
	s_nop 0
	global_load_dwordx4 v[76:79], v[76:77], off
	ds_read_b32 v102, v201 offset:256
	s_cbranch_vccnz .LBB0_186
	v_ashrrev_i32_e32 v100, 31, v114
	v_lshrrev_b32_e32 v100, 18, v100
	v_add_u32_e32 v100, v114, v100
	v_ashrrev_i32_e32 v101, 14, v100
	v_and_b32_e32 v100, 0xffffc000, v100
	v_lshl_or_b32 v104, v101, 2, s58
	v_sub_u32_e32 v100, v114, v100
	v_ashrrev_i32_e32 v105, 31, v104
	v_ashrrev_i32_e32 v101, 31, v100
	v_lshlrev_b64 v[104:105], 21, v[104:105]
	v_lshlrev_b64 v[100:101], 7, v[100:101]
	v_lshl_add_u64 v[104:105], s[0:1], 0, v[104:105]
	v_lshl_add_u64 v[100:101], v[104:105], 0, v[100:101]
	s_mov_b64 s[48:49], 0

;     __device__ __forceinline__ void operator()(const f32x4 (&acc)[2][2][4][2], const Unit& u, int wr, int wc, int fr, int fq) const {
;     ...
;             for (int it = 0; it < 8; ++it) {
;                 const int ai = it >> 2, m = it & 3;
;                 const int row = row0 + ai * HALF + m * 16;
;                 float rs = rt.get(ai, m, fr); if (isq) rs *= QSCALE_F;
;                 const f32x4 t0 = tn[0], t1 = tn[1], t2 = tn[2], t3 = tn[3];
;                 if (it < 7) { const int nrow = row0 + ((it + 1) >> 2) * HALF + ((it + 1) & 3) * 16; const f32x4* cp = (const f32x4*)(cs + (size_t)nrow * 64 + 16 * fq); tn[0] = cp[0]; tn[1] = cp[1]; tn[2] = cp[2]; tn[3] = cp[3]; }
;                 const float cc[8] = {t0[0], t0[2], t1[0], t1[2], t2[0], t2[2], t3[0], t3[2]};
;                 const float sn[8] = {t0[1], t0[3], t1[1], t1[3], t2[1], t2[3], t3[1], t3[3]};
;                 float o1[8], o2[8];
; #pragma unroll
;                 for (int n = 0; n < 2; ++n)
; #pragma unroll
;                     for (int j = 0; j < 4; ++j) {
;                         const int k = n * 4 + j;
;                         const float x1 = acc[ai][0][m][n][j] * rs, x2 = acc[ai][1][m][n][j] * rs;
;                         o1[k] = x1 * cc[k] - x2 * sn[k]; o2[k] = x2 * cc[k] + x1 * sn[k];
;                     }
;                 bf16_t* dst;
;                 if (isq) dst = Q + (size_t)row * 1024 + u.pn * 256 + wc * 64 + 8 * fq;
;                 else { const int b = row / seq, t = row - b * seq; dst = Kb + ((size_t)(b * 4 + wc) * seq + t) * 64 + 8 * fq; }
;                 *(u32x4*)dst = pack8(o1); *(u32x4*)(dst + 32) = pack8(o2);
.LBB0_188:
	s_waitcnt lgkmcnt(0)
	v_mul_f32_e32 v103, 0x3e38aa3b, v102
	v_cndmask_b32_e64 v102, v102, v103, s[6:7]
	v_pk_mul_f32 v[52:53], v[52:53], v[102:103] op_sel_hi:[1,0]
	s_waitcnt vmcnt(6)
	v_mov_b32_e32 v104, v94
	v_mov_b32_e32 v105, v96
	v_mov_b32_e32 v96, v95
	v_pk_mul_f32 v[60:61], v[60:61], v[102:103] op_sel_hi:[1,0]
	v_pk_mul_f32 v[106:107], v[104:105], v[52:53]
	v_pk_mul_f32 v[52:53], v[96:97], v[52:53]
	v_pk_fma_f32 v[94:95], v[96:97], v[60:61], v[106:107]
	v_pk_fma_f32 v[52:53], v[104:105], v[60:61], v[52:53] neg_lo:[0,0,1] neg_hi:[0,0,1]
	v_pk_mul_f32 v[60:61], v[62:63], v[102:103] op_sel_hi:[1,0]
	v_pk_mul_f32 v[54:55], v[54:55], v[102:103] op_sel_hi:[1,0]
	v_mov_b32_e32 v62, v90
	v_mov_b32_e32 v63, v92
	v_mov_b32_e32 v92, v91
	v_pk_mul_f32 v[96:97], v[62:63], v[54:55]
	v_pk_mul_f32 v[54:55], v[92:93], v[54:55]
	v_pk_fma_f32 v[90:91], v[92:93], v[60:61], v[96:97]
	v_pk_fma_f32 v[54:55], v[62:63], v[60:61], v[54:55] neg_lo:[0,0,1] neg_hi:[0,0,1]
	v_pk_mul_f32 v[48:49], v[48:49], v[102:103] op_sel_hi:[1,0]
	v_mov_b32_e32 v60, v86
	v_mov_b32_e32 v61, v88
	v_mov_b32_e32 v88, v87
	v_pk_mul_f32 v[56:57], v[56:57], v[102:103] op_sel_hi:[1,0]
	v_pk_mul_f32 v[62:63], v[60:61], v[48:49]
	v_pk_mul_f32 v[48:49], v[88:89], v[48:49]
	v_pk_fma_f32 v[62:63], v[88:89], v[56:57], v[62:63]
	v_pk_fma_f32 v[56:57], v[60:61], v[56:57], v[48:49] neg_lo:[0,0,1] neg_hi:[0,0,1]
	v_pk_mul_f32 v[48:49], v[58:59], v[102:103] op_sel_hi:[1,0]
	v_pk_mul_f32 v[50:51], v[50:51], v[102:103] op_sel_hi:[1,0]
	v_mov_b32_e32 v58, v82
	v_mov_b32_e32 v59, v84
	v_mov_b32_e32 v84, v83
	v_pk_mul_f32 v[60:61], v[58:59], v[50:51]
	v_pk_mul_f32 v[50:51], v[84:85], v[50:51]
	v_pk_fma_f32 v[60:61], v[84:85], v[48:49], v[60:61]
	v_pk_fma_f32 v[58:59], v[58:59], v[48:49], v[50:51] neg_lo:[0,0,1] neg_hi:[0,0,1]
	v_lshl_add_u64 v[82:83], v[190:191], 1, v[100:101]
	v_cvt_pk_bf16_f32 v48, v52, v53
	v_cvt_pk_bf16_f32 v49, v54, v55
	v_cvt_pk_bf16_f32 v50, v56, v57
	v_cvt_pk_bf16_f32 v51, v58, v59
	global_store_dwordx4 v[82:83], v[48:51], off nt
	s_and_b64 vcc, exec, s[4:5]
	s_mov_b64 s[48:49], -1
	v_cvt_pk_bf16_f32 v48, v94, v95
	v_cvt_pk_bf16_f32 v49, v90, v91
	v_cvt_pk_bf16_f32 v50, v62, v63
	v_cvt_pk_bf16_f32 v51, v60, v61
	global_store_dwordx4 v[82:83], v[48:51], off offset:64 nt
	v_add_u32_e32 v82, 0xa0, v192
	v_ashrrev_i32_e32 v83, 31, v82
	v_lshlrev_b64 v[48:49], 8, v[82:83]
	v_lshl_add_u64 v[48:49], s[22:23], 0, v[48:49]
	v_lshl_add_u64 v[60:61], v[188:189], 2, v[48:49]
	global_load_dwordx4 v[48:51], v[60:61], off offset:48
	global_load_dwordx4 v[52:55], v[60:61], off offset:32
	global_load_dwordx4 v[56:59], v[60:61], off offset:16
	s_nop 0
	global_load_dwordx4 v[60:63], v[60:61], off
	ds_read_b32 v86, v201 offset:320
	s_cbranch_vccnz .LBB0_190
	v_ashrrev_i32_e32 v84, 31, v98
	v_lshrrev_b32_e32 v84, 18, v84
	v_add_u32_e32 v84, v98, v84
	v_ashrrev_i32_e32 v85, 14, v84
	v_and_b32_e32 v84, 0xffffc000, v84
	v_lshl_or_b32 v88, v85, 2, s58
	v_sub_u32_e32 v84, v98, v84
	v_ashrrev_i32_e32 v89, 31, v88
	v_ashrrev_i32_e32 v85, 31, v84
	v_lshlrev_b64 v[88:89], 21, v[88:89]
	v_lshlrev_b64 v[84:85], 7, v[84:85]
	v_lshl_add_u64 v[88:89], s[0:1], 0, v[88:89]
	v_lshl_add_u64 v[84:85], v[88:89], 0, v[84:85]
	s_mov_b64 s[48:49], 0

;     __device__ __forceinline__ void operator()(const f32x4 (&acc)[2][2][4][2], const Unit& u, int wr, int wc, int fr, int fq) const {
;     ...
;             for (int it = 0; it < 8; ++it) {
;                 const int ai = it >> 2, m = it & 3;
;                 const int row = row0 + ai * HALF + m * 16;
;                 float rs = rt.get(ai, m, fr); if (isq) rs *= QSCALE_F;
;                 const f32x4 t0 = tn[0], t1 = tn[1], t2 = tn[2], t3 = tn[3];
;                 if (it < 7) { const int nrow = row0 + ((it + 1) >> 2) * HALF + ((it + 1) & 3) * 16; const f32x4* cp = (const f32x4*)(cs + (size_t)nrow * 64 + 16 * fq); tn[0] = cp[0]; tn[1] = cp[1]; tn[2] = cp[2]; tn[3] = cp[3]; }
;                 const float cc[8] = {t0[0], t0[2], t1[0], t1[2], t2[0], t2[2], t3[0], t3[2]};
;                 const float sn[8] = {t0[1], t0[3], t1[1], t1[3], t2[1], t2[3], t3[1], t3[3]};
;                 float o1[8], o2[8];
; #pragma unroll
;                 for (int n = 0; n < 2; ++n)
; #pragma unroll
;                     for (int j = 0; j < 4; ++j) {
;                         const int k = n * 4 + j;
;                         const float x1 = acc[ai][0][m][n][j] * rs, x2 = acc[ai][1][m][n][j] * rs;
;                         o1[k] = x1 * cc[k] - x2 * sn[k]; o2[k] = x2 * cc[k] + x1 * sn[k];
;                     }
;                 bf16_t* dst;
;                 if (isq) dst = Q + (size_t)row * 1024 + u.pn * 256 + wc * 64 + 8 * fq;
;                 else { const int b = row / seq, t = row - b * seq; dst = Kb + ((size_t)(b * 4 + wc) * seq + t) * 64 + 8 * fq; }
;                 *(u32x4*)dst = pack8(o1); *(u32x4*)(dst + 32) = pack8(o2);
.LBB0_192:
	s_waitcnt lgkmcnt(0)
	v_mul_f32_e32 v87, 0x3e38aa3b, v86
	v_cndmask_b32_e64 v86, v86, v87, s[6:7]
	v_pk_mul_f32 v[36:37], v[36:37], v[86:87] op_sel_hi:[1,0]
	s_waitcnt vmcnt(6)
	v_mov_b32_e32 v88, v76
	v_mov_b32_e32 v89, v78
	v_mov_b32_e32 v78, v77
	v_pk_mul_f32 v[44:45], v[44:45], v[86:87] op_sel_hi:[1,0]
	v_pk_mul_f32 v[90:91], v[88:89], v[36:37]
	v_pk_mul_f32 v[36:37], v[78:79], v[36:37]
	v_pk_fma_f32 v[76:77], v[78:79], v[44:45], v[90:91]
	v_pk_fma_f32 v[36:37], v[88:89], v[44:45], v[36:37] neg_lo:[0,0,1] neg_hi:[0,0,1]
	v_pk_mul_f32 v[44:45], v[46:47], v[86:87] op_sel_hi:[1,0]
	v_pk_mul_f32 v[38:39], v[38:39], v[86:87] op_sel_hi:[1,0]
	v_mov_b32_e32 v46, v72
	v_mov_b32_e32 v47, v74
	v_mov_b32_e32 v74, v73
	v_pk_mul_f32 v[78:79], v[46:47], v[38:39]
	v_pk_mul_f32 v[38:39], v[74:75], v[38:39]
	v_pk_fma_f32 v[72:73], v[74:75], v[44:45], v[78:79]
	v_pk_fma_f32 v[38:39], v[46:47], v[44:45], v[38:39] neg_lo:[0,0,1] neg_hi:[0,0,1]
	v_pk_mul_f32 v[32:33], v[32:33], v[86:87] op_sel_hi:[1,0]
	v_mov_b32_e32 v44, v68
	v_mov_b32_e32 v45, v70
	v_mov_b32_e32 v70, v69
	v_pk_mul_f32 v[40:41], v[40:41], v[86:87] op_sel_hi:[1,0]
	v_pk_mul_f32 v[46:47], v[44:45], v[32:33]
	v_pk_mul_f32 v[32:33], v[70:71], v[32:33]
	v_pk_fma_f32 v[46:47], v[70:71], v[40:41], v[46:47]
	v_pk_fma_f32 v[40:41], v[44:45], v[40:41], v[32:33] neg_lo:[0,0,1] neg_hi:[0,0,1]
	v_pk_mul_f32 v[32:33], v[42:43], v[86:87] op_sel_hi:[1,0]
	v_pk_mul_f32 v[34:35], v[34:35], v[86:87] op_sel_hi:[1,0]
	v_mov_b32_e32 v42, v64
	v_mov_b32_e32 v43, v66
	v_mov_b32_e32 v66, v65
	v_pk_mul_f32 v[44:45], v[42:43], v[34:35]
	v_pk_mul_f32 v[34:35], v[66:67], v[34:35]
	v_pk_fma_f32 v[44:45], v[66:67], v[32:33], v[44:45]
	v_pk_fma_f32 v[42:43], v[42:43], v[32:33], v[34:35] neg_lo:[0,0,1] neg_hi:[0,0,1]
	v_lshl_add_u64 v[64:65], v[190:191], 1, v[84:85]
	v_cvt_pk_bf16_f32 v32, v36, v37
	v_cvt_pk_bf16_f32 v33, v38, v39
	v_cvt_pk_bf16_f32 v34, v40, v41
	v_cvt_pk_bf16_f32 v35, v42, v43
	global_store_dwordx4 v[64:65], v[32:35], off nt
	s_and_b64 vcc, exec, s[4:5]
	s_mov_b64 s[48:49], -1
	v_cvt_pk_bf16_f32 v32, v76, v77
	v_cvt_pk_bf16_f32 v33, v72, v73
	v_cvt_pk_bf16_f32 v34, v46, v47
	v_cvt_pk_bf16_f32 v35, v44, v45
	global_store_dwordx4 v[64:65], v[32:35], off offset:64 nt
	v_add_u32_e32 v64, 0xb0, v192
	v_ashrrev_i32_e32 v65, 31, v64
	v_lshlrev_b64 v[32:33], 8, v[64:65]
	v_lshl_add_u64 v[32:33], s[22:23], 0, v[32:33]
	v_lshl_add_u64 v[44:45], v[188:189], 2, v[32:33]
	global_load_dwordx4 v[32:35], v[44:45], off offset:48
	global_load_dwordx4 v[36:39], v[44:45], off offset:32
	global_load_dwordx4 v[40:43], v[44:45], off offset:16
	s_nop 0
	global_load_dwordx4 v[44:47], v[44:45], off
	ds_read_b32 v68, v201 offset:384
	s_cbranch_vccnz .LBB0_194
	v_ashrrev_i32_e32 v66, 31, v82
	v_lshrrev_b32_e32 v66, 18, v66
	v_add_u32_e32 v66, v82, v66
	v_ashrrev_i32_e32 v67, 14, v66
	v_and_b32_e32 v66, 0xffffc000, v66
	v_lshl_or_b32 v70, v67, 2, s58
	v_sub_u32_e32 v66, v82, v66
	v_ashrrev_i32_e32 v71, 31, v70
	v_ashrrev_i32_e32 v67, 31, v66
	v_lshlrev_b64 v[70:71], 21, v[70:71]
	v_lshlrev_b64 v[66:67], 7, v[66:67]
	v_lshl_add_u64 v[70:71], s[0:1], 0, v[70:71]
	v_lshl_add_u64 v[66:67], v[70:71], 0, v[66:67]
	s_mov_b64 s[48:49], 0

;     __device__ __forceinline__ void operator()(const f32x4 (&acc)[2][2][4][2], const Unit& u, int wr, int wc, int fr, int fq) const {
;     ...
;             for (int it = 0; it < 8; ++it) {
;                 const int ai = it >> 2, m = it & 3;
;                 const int row = row0 + ai * HALF + m * 16;
;                 float rs = rt.get(ai, m, fr); if (isq) rs *= QSCALE_F;
;                 const f32x4 t0 = tn[0], t1 = tn[1], t2 = tn[2], t3 = tn[3];
;                 if (it < 7) { const int nrow = row0 + ((it + 1) >> 2) * HALF + ((it + 1) & 3) * 16; const f32x4* cp = (const f32x4*)(cs + (size_t)nrow * 64 + 16 * fq); tn[0] = cp[0]; tn[1] = cp[1]; tn[2] = cp[2]; tn[3] = cp[3]; }
;                 const float cc[8] = {t0[0], t0[2], t1[0], t1[2], t2[0], t2[2], t3[0], t3[2]};
;                 const float sn[8] = {t0[1], t0[3], t1[1], t1[3], t2[1], t2[3], t3[1], t3[3]};
;                 float o1[8], o2[8];
; #pragma unroll
;                 for (int n = 0; n < 2; ++n)
; #pragma unroll
;                     for (int j = 0; j < 4; ++j) {
;                         const int k = n * 4 + j;
;                         const float x1 = acc[ai][0][m][n][j] * rs, x2 = acc[ai][1][m][n][j] * rs;
;                         o1[k] = x1 * cc[k] - x2 * sn[k]; o2[k] = x2 * cc[k] + x1 * sn[k];
;                     }
;                 bf16_t* dst;
;                 if (isq) dst = Q + (size_t)row * 1024 + u.pn * 256 + wc * 64 + 8 * fq;
;                 else { const int b = row / seq, t = row - b * seq; dst = Kb + ((size_t)(b * 4 + wc) * seq + t) * 64 + 8 * fq; }
;                 *(u32x4*)dst = pack8(o1); *(u32x4*)(dst + 32) = pack8(o2);
.LBB0_196:
	s_waitcnt lgkmcnt(0)
	v_mul_f32_e32 v69, 0x3e38aa3b, v68
	v_cndmask_b32_e64 v68, v68, v69, s[6:7]
	v_pk_mul_f32 v[20:21], v[20:21], v[68:69] op_sel_hi:[1,0]
	s_waitcnt vmcnt(6)
	v_mov_b32_e32 v70, v60
	v_mov_b32_e32 v71, v62
	v_mov_b32_e32 v62, v61
	v_pk_mul_f32 v[28:29], v[28:29], v[68:69] op_sel_hi:[1,0]
	v_pk_mul_f32 v[72:73], v[70:71], v[20:21]
	v_pk_mul_f32 v[20:21], v[62:63], v[20:21]
	v_pk_fma_f32 v[60:61], v[62:63], v[28:29], v[72:73]
	v_pk_fma_f32 v[20:21], v[70:71], v[28:29], v[20:21] neg_lo:[0,0,1] neg_hi:[0,0,1]
	v_pk_mul_f32 v[28:29], v[30:31], v[68:69] op_sel_hi:[1,0]
	v_pk_mul_f32 v[22:23], v[22:23], v[68:69] op_sel_hi:[1,0]
	v_mov_b32_e32 v30, v56
	v_mov_b32_e32 v31, v58
	v_mov_b32_e32 v58, v57
	v_pk_mul_f32 v[62:63], v[30:31], v[22:23]
	v_pk_mul_f32 v[22:23], v[58:59], v[22:23]
	v_pk_fma_f32 v[56:57], v[58:59], v[28:29], v[62:63]
	v_pk_fma_f32 v[22:23], v[30:31], v[28:29], v[22:23] neg_lo:[0,0,1] neg_hi:[0,0,1]
	v_pk_mul_f32 v[16:17], v[16:17], v[68:69] op_sel_hi:[1,0]
	v_mov_b32_e32 v28, v52
	v_mov_b32_e32 v29, v54
	v_mov_b32_e32 v54, v53
	v_pk_mul_f32 v[24:25], v[24:25], v[68:69] op_sel_hi:[1,0]
	v_pk_mul_f32 v[30:31], v[28:29], v[16:17]
	v_pk_mul_f32 v[16:17], v[54:55], v[16:17]
	v_pk_fma_f32 v[30:31], v[54:55], v[24:25], v[30:31]
	v_pk_fma_f32 v[24:25], v[28:29], v[24:25], v[16:17] neg_lo:[0,0,1] neg_hi:[0,0,1]
	v_pk_mul_f32 v[16:17], v[26:27], v[68:69] op_sel_hi:[1,0]
	v_pk_mul_f32 v[18:19], v[18:19], v[68:69] op_sel_hi:[1,0]
	v_mov_b32_e32 v26, v48
	v_mov_b32_e32 v27, v50
	v_mov_b32_e32 v50, v49
	v_pk_mul_f32 v[28:29], v[26:27], v[18:19]
	v_pk_mul_f32 v[18:19], v[50:51], v[18:19]
	v_pk_fma_f32 v[28:29], v[50:51], v[16:17], v[28:29]
	v_pk_fma_f32 v[26:27], v[26:27], v[16:17], v[18:19] neg_lo:[0,0,1] neg_hi:[0,0,1]
	v_lshl_add_u64 v[48:49], v[190:191], 1, v[66:67]
	v_cvt_pk_bf16_f32 v16, v20, v21
	v_cvt_pk_bf16_f32 v17, v22, v23
	v_cvt_pk_bf16_f32 v18, v24, v25
	v_cvt_pk_bf16_f32 v19, v26, v27
	global_store_dwordx4 v[48:49], v[16:19], off nt
	ds_read_b32 v18, v201 offset:448
	v_cvt_pk_bf16_f32 v20, v60, v61
	v_cvt_pk_bf16_f32 v21, v56, v57
	v_cvt_pk_bf16_f32 v22, v30, v31
	v_cvt_pk_bf16_f32 v23, v28, v29
	s_and_b64 vcc, exec, s[4:5]
	s_mov_b64 s[4:5], -1
	global_store_dwordx4 v[48:49], v[20:23], off offset:64 nt
	s_cbranch_vccnz .LBB0_198
	v_ashrrev_i32_e32 v16, 31, v64
	v_lshrrev_b32_e32 v16, 18, v16
	v_add_u32_e32 v16, v64, v16
	v_ashrrev_i32_e32 v17, 14, v16
	v_and_b32_e32 v16, 0xffffc000, v16
	v_lshl_or_b32 v20, v17, 2, s58
	v_sub_u32_e32 v16, v64, v16
	v_ashrrev_i32_e32 v21, 31, v20
	v_ashrrev_i32_e32 v17, 31, v16
	v_lshlrev_b64 v[20:21], 21, v[20:21]
	v_lshlrev_b64 v[16:17], 7, v[16:17]
	v_lshl_add_u64 v[20:21], s[0:1], 0, v[20:21]
	v_lshl_add_u64 v[16:17], v[20:21], 0, v[16:17]
	s_mov_b64 s[4:5], 0

;     __device__ __forceinline__ void operator()(const f32x4 (&acc)[2][2][4][2], const Unit& u, int wr, int wc, int fr, int fq) const {
;     ...
;             for (int it = 0; it < 8; ++it) {
;                 const int ai = it >> 2, m = it & 3;
;                 const int row = row0 + ai * HALF + m * 16;
;                 float rs = rt.get(ai, m, fr); if (isq) rs *= QSCALE_F;
;                 const f32x4 t0 = tn[0], t1 = tn[1], t2 = tn[2], t3 = tn[3];
;                 if (it < 7) { const int nrow = row0 + ((it + 1) >> 2) * HALF + ((it + 1) & 3) * 16; const f32x4* cp = (const f32x4*)(cs + (size_t)nrow * 64 + 16 * fq); tn[0] = cp[0]; tn[1] = cp[1]; tn[2] = cp[2]; tn[3] = cp[3]; }
;                 const float cc[8] = {t0[0], t0[2], t1[0], t1[2], t2[0], t2[2], t3[0], t3[2]};
;                 const float sn[8] = {t0[1], t0[3], t1[1], t1[3], t2[1], t2[3], t3[1], t3[3]};
;                 float o1[8], o2[8];
; #pragma unroll
;                 for (int n = 0; n < 2; ++n)
; #pragma unroll
;                     for (int j = 0; j < 4; ++j) {
;                         const int k = n * 4 + j;
;                         const float x1 = acc[ai][0][m][n][j] * rs, x2 = acc[ai][1][m][n][j] * rs;
;                         o1[k] = x1 * cc[k] - x2 * sn[k]; o2[k] = x2 * cc[k] + x1 * sn[k];
;                     }
;                 bf16_t* dst;
;                 if (isq) dst = Q + (size_t)row * 1024 + u.pn * 256 + wc * 64 + 8 * fq;
;                 else { const int b = row / seq, t = row - b * seq; dst = Kb + ((size_t)(b * 4 + wc) * seq + t) * 64 + 8 * fq; }
;                 *(u32x4*)dst = pack8(o1); *(u32x4*)(dst + 32) = pack8(o2);
.LBB0_200:
	s_waitcnt lgkmcnt(0)
	v_mul_f32_e32 v19, 0x3e38aa3b, v18
	v_cndmask_b32_e64 v18, v18, v19, s[6:7]
	v_pk_mul_f32 v[4:5], v[4:5], v[18:19] op_sel_hi:[1,0]
	s_waitcnt vmcnt(2)
	v_mov_b32_e32 v20, v44
	v_mov_b32_e32 v21, v46
	v_mov_b32_e32 v46, v45
	v_pk_mul_f32 v[12:13], v[12:13], v[18:19] op_sel_hi:[1,0]
	v_pk_mul_f32 v[22:23], v[20:21], v[4:5]
	v_pk_mul_f32 v[4:5], v[46:47], v[4:5]
	v_pk_fma_f32 v[22:23], v[46:47], v[12:13], v[22:23]
	v_pk_fma_f32 v[4:5], v[20:21], v[12:13], v[4:5] neg_lo:[0,0,1] neg_hi:[0,0,1]
	v_pk_mul_f32 v[12:13], v[14:15], v[18:19] op_sel_hi:[1,0]
	v_pk_mul_f32 v[6:7], v[6:7], v[18:19] op_sel_hi:[1,0]
	v_mov_b32_e32 v14, v40
	v_mov_b32_e32 v15, v42
	v_mov_b32_e32 v42, v41
	v_pk_mul_f32 v[20:21], v[14:15], v[6:7]
	v_pk_mul_f32 v[6:7], v[42:43], v[6:7]
	v_pk_fma_f32 v[20:21], v[42:43], v[12:13], v[20:21]
	v_pk_fma_f32 v[6:7], v[14:15], v[12:13], v[6:7] neg_lo:[0,0,1] neg_hi:[0,0,1]
	v_pk_mul_f32 v[0:1], v[0:1], v[18:19] op_sel_hi:[1,0]
	v_mov_b32_e32 v12, v36
	v_mov_b32_e32 v13, v38
	v_mov_b32_e32 v38, v37
	v_pk_mul_f32 v[8:9], v[8:9], v[18:19] op_sel_hi:[1,0]
	v_pk_mul_f32 v[14:15], v[12:13], v[0:1]
	v_pk_mul_f32 v[0:1], v[38:39], v[0:1]
	v_pk_fma_f32 v[14:15], v[38:39], v[8:9], v[14:15]
	v_pk_fma_f32 v[8:9], v[12:13], v[8:9], v[0:1] neg_lo:[0,0,1] neg_hi:[0,0,1]
	v_pk_mul_f32 v[0:1], v[10:11], v[18:19] op_sel_hi:[1,0]
	v_pk_mul_f32 v[2:3], v[2:3], v[18:19] op_sel_hi:[1,0]
	v_mov_b32_e32 v10, v32
	v_mov_b32_e32 v11, v34
	v_mov_b32_e32 v34, v33
	v_pk_mul_f32 v[12:13], v[10:11], v[2:3]
	v_pk_mul_f32 v[2:3], v[34:35], v[2:3]
	v_pk_fma_f32 v[12:13], v[34:35], v[0:1], v[12:13]
	v_pk_fma_f32 v[10:11], v[10:11], v[0:1], v[2:3] neg_lo:[0,0,1] neg_hi:[0,0,1]
	v_lshl_add_u64 v[16:17], v[190:191], 1, v[16:17]
	v_cvt_pk_bf16_f32 v0, v4, v5
	v_cvt_pk_bf16_f32 v1, v6, v7
	v_cvt_pk_bf16_f32 v2, v8, v9
	v_cvt_pk_bf16_f32 v3, v10, v11
	global_store_dwordx4 v[16:17], v[0:3], off nt
	s_mov_b32 s5, s66
	s_nop 0
	v_cvt_pk_bf16_f32 v0, v22, v23
	v_cvt_pk_bf16_f32 v1, v20, v21
	v_cvt_pk_bf16_f32 v2, v14, v15
	v_cvt_pk_bf16_f32 v3, v12, v13
	global_store_dwordx4 v[16:17], v[0:3], off offset:64 nt
	s_mov_b32 s66, s5
	s_andn2_b64 vcc, exec, s[42:43]
	s_mov_b64 s[4:5], -1
	s_cbranch_vccnz .LBB0_152
